# speedup vs baseline: 1.0164x; 1.0044x over previous
; #define WAIT_V(n) asm volatile("s_waitcnt vmcnt(" #n ")" ::: "memory")
; #define WAIT_L(n) asm volatile("s_waitcnt lgkmcnt(" #n ")" ::: "memory")
; #define BAR __builtin_amdgcn_s_barrier()
; #define SCHED __builtin_amdgcn_sched_barrier(0)
; #define STAGE_A(b, h, kt)                                        \
;   do {                                                           \
;     const char* _g = Ab + (h) * halfK + (long)(kt) * 128;        \
;     GLDS2(_g, (unsigned)(((b) * 2 + (h)) * 16384));              \
;   } while (0)
; #define STAGE_B(b, h, kt)                                        \
;   do {                                                           \
;     const char* _g = Bb + (h) * halfK + (long)(kt) * 128;        \
;     GLDS2(_g, (unsigned)(65536 + ((b) * 2 + (h)) * 16384));      \
;   } while (0)
; #define LDA(dst, b, h)                                                                                   \
;   _Pragma("unroll") for (int m = 0; m < 4; ++m) _Pragma("unroll") for (int k = 0; k < 2; ++k) dst[m][k] = \
;       *reinterpret_cast<const bf16x8*>(aRd + ((b) * 2 + (h)) * 16384 + m * 2048 + k * 1024)
; #define LDB(dst, b, h)                                                                                   \
;   _Pragma("unroll") for (int n = 0; n < 2; ++n) _Pragma("unroll") for (int k = 0; k < 2; ++k) dst[n][k] = \
;       *reinterpret_cast<const bf16x8*>(bRd + ((b) * 2 + (h)) * 16384 + n * 2048 + k * 1024)
; template <int EPI> ...
;     ...
;     LDB(B0, 0, 0);
;     SCHED;
;     LDA(At, 0, 0);
;     STAGE_A(1, 1, t + 1);
;     WAIT_L(8);
;     BAR;
;     WAIT_L(0);
;     MMA(0, 0, At, B0);
;     BAR;
;     SCHED;
;     LDB(B1, 0, 1);
;     STAGE_B(0, 0, t + 2);
;     BAR;
;     WAIT_L(0);
;     MMA(0, 1, At, B1);
;     BAR;
;     LDA(At, 0, 1);
;     STAGE_A(0, 0, t + 2);
;     BAR;
;     WAIT_L(0);
;     MMA(1, 0, At, B0);
;     BAR;
;     SCHED;
;     STAGE_B(0, 1, t + 2);
;     WAIT_V(6);
;     BAR;
.LBB0_114:
	ds_read_b128 v[138:141], v137
	ds_read_b128 v[142:145], v137 offset:1024
	ds_read_b128 v[146:149], v137 offset:2048
	ds_read_b128 v[150:153], v137 offset:3072
	ds_read_b128 v[154:157], v136
	ds_read_b128 v[158:161], v136 offset:1024
	ds_read_b128 v[162:165], v136 offset:2048
	ds_read_b128 v[166:169], v136 offset:3072
	ds_read_b128 v[170:173], v136 offset:4096
	ds_read_b128 v[174:177], v136 offset:5120
	ds_read_b128 v[178:181], v136 offset:6144
	ds_read_b128 v[182:185], v136 offset:7168
	s_add_u32 s22, s11, s12
	s_addc_u32 s23, s37, s13
	s_add_u32 s74, s22, 0x80
	s_addc_u32 s75, s23, 0
	s_mov_b32 m0, s77
	s_nop 0
	global_load_lds_dwordx4 v132, s[74:75]
	s_nop 0
	s_mov_b32 m0, s64
	s_nop 0
	global_load_lds_dwordx4 v130, s[74:75]
	s_waitcnt lgkmcnt(8)
	s_barrier
	s_waitcnt lgkmcnt(0)
	s_setprio 1
	v_mfma_f32_16x16x32_bf16 v[126:129], v[138:141], v[154:157], v[126:129]
	v_mfma_f32_16x16x32_bf16 v[126:129], v[142:145], v[158:161], v[126:129]
	v_mfma_f32_16x16x32_bf16 v[122:125], v[150:153], v[158:161], v[122:125]
	v_mfma_f32_16x16x32_bf16 v[122:125], v[146:149], v[154:157], v[122:125]
	v_mfma_f32_16x16x32_bf16 v[114:117], v[146:149], v[162:165], v[114:117]
	v_mfma_f32_16x16x32_bf16 v[114:117], v[150:153], v[166:169], v[114:117]
	v_mfma_f32_16x16x32_bf16 v[118:121], v[142:145], v[166:169], v[118:121]
	v_mfma_f32_16x16x32_bf16 v[118:121], v[138:141], v[162:165], v[118:121]
	v_mfma_f32_16x16x32_bf16 v[110:113], v[138:141], v[170:173], v[110:113]
	v_mfma_f32_16x16x32_bf16 v[110:113], v[142:145], v[174:177], v[110:113]
	v_mfma_f32_16x16x32_bf16 v[106:109], v[150:153], v[174:177], v[106:109]
	v_mfma_f32_16x16x32_bf16 v[106:109], v[146:149], v[170:173], v[106:109]
	v_mfma_f32_16x16x32_bf16 v[98:101], v[146:149], v[178:181], v[98:101]
	v_mfma_f32_16x16x32_bf16 v[98:101], v[150:153], v[182:185], v[98:101]
	v_mfma_f32_16x16x32_bf16 v[102:105], v[142:145], v[182:185], v[102:105]
	v_mfma_f32_16x16x32_bf16 v[102:105], v[138:141], v[178:181], v[102:105]
	s_setprio 0
	s_barrier
	ds_read_b128 v[186:189], v137 offset:16384
	ds_read_b128 v[196:199], v137 offset:17408
	ds_read_b128 v[212:215], v137 offset:18432
	ds_read_b128 v[220:223], v137 offset:19456
	s_add_u32 s49, s98, s12
	s_addc_u32 s54, s99, s13
	s_add_u32 s74, s49, 0x100
	s_addc_u32 s75, s54, 0
	s_mov_b32 m0, s20
	s_nop 0
	global_load_lds_dwordx4 v132, s[74:75]
	s_nop 0
	s_mov_b32 m0, s21
	s_nop 0
	global_load_lds_dwordx4 v130, s[74:75]
	s_barrier
	s_waitcnt lgkmcnt(0)
	s_setprio 1
	v_mfma_f32_16x16x32_bf16 v[94:97], v[186:189], v[154:157], v[94:97]
	v_mfma_f32_16x16x32_bf16 v[94:97], v[196:199], v[158:161], v[94:97]
	v_mfma_f32_16x16x32_bf16 v[90:93], v[220:223], v[158:161], v[90:93]
	v_mfma_f32_16x16x32_bf16 v[90:93], v[212:215], v[154:157], v[90:93]
	v_mfma_f32_16x16x32_bf16 v[82:85], v[212:215], v[162:165], v[82:85]
	v_mfma_f32_16x16x32_bf16 v[82:85], v[220:223], v[166:169], v[82:85]
	v_mfma_f32_16x16x32_bf16 v[86:89], v[196:199], v[166:169], v[86:89]
	v_mfma_f32_16x16x32_bf16 v[86:89], v[186:189], v[162:165], v[86:89]
	v_mfma_f32_16x16x32_bf16 v[78:81], v[186:189], v[170:173], v[78:81]
	v_mfma_f32_16x16x32_bf16 v[78:81], v[196:199], v[174:177], v[78:81]
	v_mfma_f32_16x16x32_bf16 v[74:77], v[220:223], v[174:177], v[74:77]
	v_mfma_f32_16x16x32_bf16 v[74:77], v[212:215], v[170:173], v[74:77]
	v_mfma_f32_16x16x32_bf16 v[66:69], v[212:215], v[178:181], v[66:69]
	v_mfma_f32_16x16x32_bf16 v[66:69], v[220:223], v[182:185], v[66:69]
	v_mfma_f32_16x16x32_bf16 v[70:73], v[196:199], v[182:185], v[70:73]
	v_mfma_f32_16x16x32_bf16 v[70:73], v[186:189], v[178:181], v[70:73]
	s_setprio 0
	s_barrier
	ds_read_b128 v[154:157], v136 offset:16384
	ds_read_b128 v[158:161], v136 offset:17408
	ds_read_b128 v[162:165], v136 offset:18432
	ds_read_b128 v[166:169], v136 offset:19456
	ds_read_b128 v[170:173], v136 offset:20480
	ds_read_b128 v[174:177], v136 offset:21504
	ds_read_b128 v[178:181], v136 offset:22528
	ds_read_b128 v[182:185], v136 offset:23552
	s_add_u32 s60, s96, s12
	s_addc_u32 s68, s97, s13
	s_add_u32 s74, s60, 0x100
	s_addc_u32 s75, s68, 0
	s_mov_b32 m0, s2
	s_nop 0
	global_load_lds_dwordx4 v132, s[74:75]
	s_nop 0
	s_mov_b32 m0, s38
	s_nop 0
	global_load_lds_dwordx4 v130, s[74:75]
	s_barrier
	s_waitcnt lgkmcnt(0)
	s_setprio 1
	v_mfma_f32_16x16x32_bf16 v[62:65], v[138:141], v[154:157], v[62:65]
	v_mfma_f32_16x16x32_bf16 v[62:65], v[142:145], v[158:161], v[62:65]
	v_mfma_f32_16x16x32_bf16 v[58:61], v[150:153], v[158:161], v[58:61]
	v_mfma_f32_16x16x32_bf16 v[58:61], v[146:149], v[154:157], v[58:61]
	v_mfma_f32_16x16x32_bf16 v[50:53], v[146:149], v[162:165], v[50:53]
	v_mfma_f32_16x16x32_bf16 v[50:53], v[150:153], v[166:169], v[50:53]
	v_mfma_f32_16x16x32_bf16 v[54:57], v[142:145], v[166:169], v[54:57]
	v_mfma_f32_16x16x32_bf16 v[54:57], v[138:141], v[162:165], v[54:57]
	v_mfma_f32_16x16x32_bf16 v[46:49], v[138:141], v[170:173], v[46:49]
	v_mfma_f32_16x16x32_bf16 v[46:49], v[142:145], v[174:177], v[46:49]
	v_mfma_f32_16x16x32_bf16 v[42:45], v[150:153], v[174:177], v[42:45]
	v_mfma_f32_16x16x32_bf16 v[42:45], v[146:149], v[170:173], v[42:45]
	v_mfma_f32_16x16x32_bf16 v[34:37], v[146:149], v[178:181], v[34:37]
	v_mfma_f32_16x16x32_bf16 v[34:37], v[150:153], v[182:185], v[34:37]
	v_mfma_f32_16x16x32_bf16 v[38:41], v[142:145], v[182:185], v[38:41]
	v_mfma_f32_16x16x32_bf16 v[38:41], v[138:141], v[178:181], v[38:41]
	s_setprio 0
	s_barrier
	s_add_u32 s69, s7, s12
	s_addc_u32 s76, s8, s13
	s_add_u32 s74, s69, 0x100
	s_addc_u32 s75, s76, 0
	s_mov_b32 m0, s39
	s_nop 0
	global_load_lds_dwordx4 v132, s[74:75]
	s_nop 0
	s_mov_b32 m0, s28
	s_nop 0
	global_load_lds_dwordx4 v130, s[74:75]
	s_waitcnt vmcnt(6)
	s_barrier
; #define WAIT_L(n) asm volatile("s_waitcnt lgkmcnt(" #n ")" ::: "memory")
; #define BAR __builtin_amdgcn_s_barrier()
; #define SCHED __builtin_amdgcn_sched_barrier(0)
; #define STAGE_A(b, h, kt)                                        \
;   do {                                                           \
;     const char* _g = Ab + (h) * halfK + (long)(kt) * 128;        \
;     GLDS2(_g, (unsigned)(((b) * 2 + (h)) * 16384));              \
;   } while (0)
; #define STAGE_B(b, h, kt)                                        \
;   do {                                                           \
;     const char* _g = Bb + (h) * halfK + (long)(kt) * 128;        \
;     GLDS2(_g, (unsigned)(65536 + ((b) * 2 + (h)) * 16384));      \
;   } while (0)
; #define LDA(dst, b, h)                                                                                   \
;   _Pragma("unroll") for (int m = 0; m < 4; ++m) _Pragma("unroll") for (int k = 0; k < 2; ++k) dst[m][k] = \
;       *reinterpret_cast<const bf16x8*>(aRd + ((b) * 2 + (h)) * 16384 + m * 2048 + k * 1024)
; #define LDB(dst, b, h)                                                                                   \
;   _Pragma("unroll") for (int n = 0; n < 2; ++n) _Pragma("unroll") for (int k = 0; k < 2; ++k) dst[n][k] = \
;       *reinterpret_cast<const bf16x8*>(bRd + ((b) * 2 + (h)) * 16384 + n * 2048 + k * 1024)
; template <int EPI> ...
;     ...
;     MMA(1, 1, At, B1);
;     BAR;
;     LDB(B0, 1, 0);
;     SCHED;
;     LDA(At, 1, 0);
;     STAGE_A(0, 1, t + 2);
;     WAIT_L(8);
;     BAR;
;     WAIT_L(0);
;     MMA(0, 0, At, B0);
;     BAR;
;     SCHED;
;     LDB(B1, 1, 1);
;     STAGE_B(1, 0, t + 3);
;     BAR;
;     WAIT_L(0);
;     MMA(0, 1, At, B1);
;     BAR;
;     LDA(At, 1, 1);
;     STAGE_A(1, 0, t + 3);
;     BAR;
;     WAIT_L(0);
;     MMA(1, 0, At, B0);
;     BAR;
;     SCHED;
;     STAGE_B(1, 1, t + 3);
	s_setprio 1
	v_mfma_f32_16x16x32_bf16 v[30:33], v[186:189], v[154:157], v[30:33]
	v_mfma_f32_16x16x32_bf16 v[30:33], v[196:199], v[158:161], v[30:33]
	v_mfma_f32_16x16x32_bf16 v[26:29], v[220:223], v[158:161], v[26:29]
	v_mfma_f32_16x16x32_bf16 v[26:29], v[212:215], v[154:157], v[26:29]
	v_mfma_f32_16x16x32_bf16 v[18:21], v[212:215], v[162:165], v[18:21]
	v_mfma_f32_16x16x32_bf16 v[18:21], v[220:223], v[166:169], v[18:21]
	v_mfma_f32_16x16x32_bf16 v[22:25], v[196:199], v[166:169], v[22:25]
	v_mfma_f32_16x16x32_bf16 v[22:25], v[186:189], v[162:165], v[22:25]
	v_mfma_f32_16x16x32_bf16 v[14:17], v[186:189], v[170:173], v[14:17]
	v_mfma_f32_16x16x32_bf16 v[14:17], v[196:199], v[174:177], v[14:17]
	v_mfma_f32_16x16x32_bf16 v[10:13], v[220:223], v[174:177], v[10:13]
	v_mfma_f32_16x16x32_bf16 v[10:13], v[212:215], v[170:173], v[10:13]
	v_mfma_f32_16x16x32_bf16 v[2:5], v[212:215], v[178:181], v[2:5]
	v_mfma_f32_16x16x32_bf16 v[2:5], v[220:223], v[182:185], v[2:5]
	v_mfma_f32_16x16x32_bf16 v[6:9], v[196:199], v[182:185], v[6:9]
	v_mfma_f32_16x16x32_bf16 v[6:9], v[186:189], v[178:181], v[6:9]
	s_setprio 0
	s_barrier
	ds_read_b128 v[138:141], v137 offset:32768
	ds_read_b128 v[142:145], v137 offset:33792
	ds_read_b128 v[146:149], v137 offset:34816
	ds_read_b128 v[150:153], v137 offset:35840
	ds_read_b128 v[154:157], v136 offset:32768
	ds_read_b128 v[158:161], v136 offset:33792
	ds_read_b128 v[162:165], v136 offset:34816
	ds_read_b128 v[166:169], v136 offset:35840
	ds_read_b128 v[170:173], v136 offset:36864
	ds_read_b128 v[174:177], v136 offset:37888
	ds_read_b128 v[178:181], v136 offset:38912
	ds_read_b128 v[182:185], v136 offset:39936
	s_add_u32 s74, s22, 0x100
	s_addc_u32 s75, s23, 0
	s_mov_b32 m0, s29
	s_nop 0
	global_load_lds_dwordx4 v132, s[74:75]
	s_nop 0
	s_mov_b32 m0, s62
	s_nop 0
	global_load_lds_dwordx4 v130, s[74:75]
	s_waitcnt lgkmcnt(8)
	s_barrier
	s_waitcnt lgkmcnt(0)
	s_setprio 1
	v_mfma_f32_16x16x32_bf16 v[126:129], v[138:141], v[154:157], v[126:129]
	v_mfma_f32_16x16x32_bf16 v[126:129], v[142:145], v[158:161], v[126:129]
	v_mfma_f32_16x16x32_bf16 v[122:125], v[150:153], v[158:161], v[122:125]
	v_mfma_f32_16x16x32_bf16 v[122:125], v[146:149], v[154:157], v[122:125]
	v_mfma_f32_16x16x32_bf16 v[114:117], v[146:149], v[162:165], v[114:117]
	v_mfma_f32_16x16x32_bf16 v[114:117], v[150:153], v[166:169], v[114:117]
	v_mfma_f32_16x16x32_bf16 v[118:121], v[142:145], v[166:169], v[118:121]
	v_mfma_f32_16x16x32_bf16 v[118:121], v[138:141], v[162:165], v[118:121]
	v_mfma_f32_16x16x32_bf16 v[110:113], v[138:141], v[170:173], v[110:113]
	v_mfma_f32_16x16x32_bf16 v[110:113], v[142:145], v[174:177], v[110:113]
	v_mfma_f32_16x16x32_bf16 v[106:109], v[150:153], v[174:177], v[106:109]
	v_mfma_f32_16x16x32_bf16 v[106:109], v[146:149], v[170:173], v[106:109]
	v_mfma_f32_16x16x32_bf16 v[98:101], v[146:149], v[178:181], v[98:101]
	v_mfma_f32_16x16x32_bf16 v[98:101], v[150:153], v[182:185], v[98:101]
	v_mfma_f32_16x16x32_bf16 v[102:105], v[142:145], v[182:185], v[102:105]
	v_mfma_f32_16x16x32_bf16 v[102:105], v[138:141], v[178:181], v[102:105]
	s_setprio 0
	s_barrier
	ds_read_b128 v[186:189], v137 offset:49152
	ds_read_b128 v[196:199], v137 offset:50176
	ds_read_b128 v[212:215], v137 offset:51200
	ds_read_b128 v[220:223], v137 offset:52224
	s_add_u32 s74, s49, 0x180
	s_addc_u32 s75, s54, 0
	s_mov_b32 m0, s50
	s_nop 0
	global_load_lds_dwordx4 v132, s[74:75]
	s_nop 0
	s_mov_b32 m0, s51
	s_nop 0
	global_load_lds_dwordx4 v130, s[74:75]
	s_barrier
	s_waitcnt lgkmcnt(0)
	s_setprio 1
	v_mfma_f32_16x16x32_bf16 v[94:97], v[186:189], v[154:157], v[94:97]
	v_mfma_f32_16x16x32_bf16 v[94:97], v[196:199], v[158:161], v[94:97]
	v_mfma_f32_16x16x32_bf16 v[90:93], v[220:223], v[158:161], v[90:93]
	v_mfma_f32_16x16x32_bf16 v[90:93], v[212:215], v[154:157], v[90:93]
	v_mfma_f32_16x16x32_bf16 v[82:85], v[212:215], v[162:165], v[82:85]
	v_mfma_f32_16x16x32_bf16 v[82:85], v[220:223], v[166:169], v[82:85]
	v_mfma_f32_16x16x32_bf16 v[86:89], v[196:199], v[166:169], v[86:89]
	v_mfma_f32_16x16x32_bf16 v[86:89], v[186:189], v[162:165], v[86:89]
	v_mfma_f32_16x16x32_bf16 v[78:81], v[186:189], v[170:173], v[78:81]
	v_mfma_f32_16x16x32_bf16 v[78:81], v[196:199], v[174:177], v[78:81]
	v_mfma_f32_16x16x32_bf16 v[74:77], v[220:223], v[174:177], v[74:77]
	v_mfma_f32_16x16x32_bf16 v[74:77], v[212:215], v[170:173], v[74:77]
	v_mfma_f32_16x16x32_bf16 v[66:69], v[212:215], v[178:181], v[66:69]
	v_mfma_f32_16x16x32_bf16 v[66:69], v[220:223], v[182:185], v[66:69]
	v_mfma_f32_16x16x32_bf16 v[70:73], v[196:199], v[182:185], v[70:73]
	v_mfma_f32_16x16x32_bf16 v[70:73], v[186:189], v[178:181], v[70:73]
	s_setprio 0
	s_barrier
	ds_read_b128 v[154:157], v136 offset:49152
	ds_read_b128 v[158:161], v136 offset:50176
	ds_read_b128 v[162:165], v136 offset:51200
	ds_read_b128 v[166:169], v136 offset:52224
	ds_read_b128 v[170:173], v136 offset:53248
	ds_read_b128 v[174:177], v136 offset:54272
	ds_read_b128 v[178:181], v136 offset:55296
	ds_read_b128 v[182:185], v136 offset:56320
	s_add_u32 s74, s60, 0x180
	s_addc_u32 s75, s68, 0
	s_mov_b32 m0, s63
	s_nop 0
	global_load_lds_dwordx4 v132, s[74:75]
	s_nop 0
	s_mov_b32 m0, s6
	s_nop 0
	global_load_lds_dwordx4 v130, s[74:75]
	s_barrier
; #define WAIT_V(n) asm volatile("s_waitcnt vmcnt(" #n ")" ::: "memory")
; #define WAIT_L(n) asm volatile("s_waitcnt lgkmcnt(" #n ")" ::: "memory")
; #define BAR __builtin_amdgcn_s_barrier()
; #define SCHED __builtin_amdgcn_sched_barrier(0)
; #define STAGE_A(b, h, kt)                                        \
;   do {                                                           \
;     const char* _g = Ab + (h) * halfK + (long)(kt) * 128;        \
;     GLDS2(_g, (unsigned)(((b) * 2 + (h)) * 16384));              \
;   } while (0)
; #define STAGE_B(b, h, kt)                                        \
;   do {                                                           \
;     const char* _g = Bb + (h) * halfK + (long)(kt) * 128;        \
;     GLDS2(_g, (unsigned)(65536 + ((b) * 2 + (h)) * 16384));      \
;   } while (0)
; #define LDA(dst, b, h)                                                                                   \
;   _Pragma("unroll") for (int m = 0; m < 4; ++m) _Pragma("unroll") for (int k = 0; k < 2; ++k) dst[m][k] = \
;       *reinterpret_cast<const bf16x8*>(aRd + ((b) * 2 + (h)) * 16384 + m * 2048 + k * 1024)
; #define LDB(dst, b, h)                                                                                   \
;   _Pragma("unroll") for (int n = 0; n < 2; ++n) _Pragma("unroll") for (int k = 0; k < 2; ++k) dst[n][k] = \
;       *reinterpret_cast<const bf16x8*>(bRd + ((b) * 2 + (h)) * 16384 + n * 2048 + k * 1024)
; template <int EPI> ...
;     ...
;     MMA(1, 0, At, B0);
;     BAR;
;     SCHED;
;     STAGE_B(1, 1, t + 3);
;     WAIT_V(6);
;     BAR;
;     MMA(1, 1, At, B1);
;     BAR;
;   }
;   {
;     LDB(B0, 0, 0);
;     LDA(At, 0, 0);
;     STAGE_A(1, 1, nt - 1);
;     BAR;
;     WAIT_L(0);
;     MMA(0, 0, At, B0);
;     BAR;
;     LDB(B1, 0, 1);
;     BAR;
;     WAIT_L(0);
;     MMA(0, 1, At, B1);
;     BAR;
	s_waitcnt lgkmcnt(0)
	s_setprio 1
	v_mfma_f32_16x16x32_bf16 v[62:65], v[138:141], v[154:157], v[62:65]
	v_mfma_f32_16x16x32_bf16 v[62:65], v[142:145], v[158:161], v[62:65]
	v_mfma_f32_16x16x32_bf16 v[58:61], v[150:153], v[158:161], v[58:61]
	v_mfma_f32_16x16x32_bf16 v[58:61], v[146:149], v[154:157], v[58:61]
	v_mfma_f32_16x16x32_bf16 v[50:53], v[146:149], v[162:165], v[50:53]
	v_mfma_f32_16x16x32_bf16 v[50:53], v[150:153], v[166:169], v[50:53]
	v_mfma_f32_16x16x32_bf16 v[54:57], v[142:145], v[166:169], v[54:57]
	v_mfma_f32_16x16x32_bf16 v[54:57], v[138:141], v[162:165], v[54:57]
	v_mfma_f32_16x16x32_bf16 v[46:49], v[138:141], v[170:173], v[46:49]
	v_mfma_f32_16x16x32_bf16 v[46:49], v[142:145], v[174:177], v[46:49]
	v_mfma_f32_16x16x32_bf16 v[42:45], v[150:153], v[174:177], v[42:45]
	v_mfma_f32_16x16x32_bf16 v[42:45], v[146:149], v[170:173], v[42:45]
	v_mfma_f32_16x16x32_bf16 v[34:37], v[146:149], v[178:181], v[34:37]
	v_mfma_f32_16x16x32_bf16 v[34:37], v[150:153], v[182:185], v[34:37]
	v_mfma_f32_16x16x32_bf16 v[38:41], v[142:145], v[182:185], v[38:41]
	v_mfma_f32_16x16x32_bf16 v[38:41], v[138:141], v[178:181], v[38:41]
	s_setprio 0
	s_barrier
	s_add_u32 s74, s69, 0x180
	s_addc_u32 s75, s76, 0
	s_mov_b32 m0, s9
	s_nop 0
	global_load_lds_dwordx4 v132, s[74:75]
	s_nop 0
	s_mov_b32 m0, s10
	s_nop 0
	global_load_lds_dwordx4 v130, s[74:75]
	s_waitcnt vmcnt(6)
	s_barrier
	s_setprio 1
	v_mfma_f32_16x16x32_bf16 v[30:33], v[186:189], v[154:157], v[30:33]
	v_mfma_f32_16x16x32_bf16 v[30:33], v[196:199], v[158:161], v[30:33]
	v_mfma_f32_16x16x32_bf16 v[26:29], v[220:223], v[158:161], v[26:29]
	v_mfma_f32_16x16x32_bf16 v[26:29], v[212:215], v[154:157], v[26:29]
	v_mfma_f32_16x16x32_bf16 v[18:21], v[212:215], v[162:165], v[18:21]
	v_mfma_f32_16x16x32_bf16 v[18:21], v[220:223], v[166:169], v[18:21]
	v_mfma_f32_16x16x32_bf16 v[22:25], v[196:199], v[166:169], v[22:25]
	v_mfma_f32_16x16x32_bf16 v[22:25], v[186:189], v[162:165], v[22:25]
	v_mfma_f32_16x16x32_bf16 v[14:17], v[186:189], v[170:173], v[14:17]
	v_mfma_f32_16x16x32_bf16 v[14:17], v[196:199], v[174:177], v[14:17]
	v_mfma_f32_16x16x32_bf16 v[10:13], v[220:223], v[174:177], v[10:13]
	v_mfma_f32_16x16x32_bf16 v[10:13], v[212:215], v[170:173], v[10:13]
	v_mfma_f32_16x16x32_bf16 v[2:5], v[212:215], v[178:181], v[2:5]
	v_mfma_f32_16x16x32_bf16 v[2:5], v[220:223], v[182:185], v[2:5]
	v_mfma_f32_16x16x32_bf16 v[6:9], v[196:199], v[182:185], v[6:9]
	v_mfma_f32_16x16x32_bf16 v[6:9], v[186:189], v[178:181], v[6:9]
	s_setprio 0
	s_add_i32 s91, s91, 2
	s_add_u32 s12, s12, 0x100
	s_addc_u32 s13, s13, 0
	s_cmp_lt_u32 s91, 28
	s_barrier
	s_cbranch_scc1 .LBB0_114
	ds_read_b128 v[138:141], v137
	ds_read_b128 v[142:145], v137 offset:1024
	ds_read_b128 v[146:149], v137 offset:2048
	ds_read_b128 v[150:153], v137 offset:3072
	ds_read_b128 v[154:157], v136
	ds_read_b128 v[158:161], v136 offset:1024
	ds_read_b128 v[162:165], v136 offset:2048
	ds_read_b128 v[166:169], v136 offset:3072
	ds_read_b128 v[170:173], v136 offset:4096
	ds_read_b128 v[174:177], v136 offset:5120
	ds_read_b128 v[178:181], v136 offset:6144
	ds_read_b128 v[182:185], v136 offset:7168
	s_add_u32 s6, s96, 0x80f80
	s_addc_u32 s7, s97, 0
	s_mov_b32 m0, s77
	s_nop 0
	global_load_lds_dwordx4 v132, s[6:7]
	s_nop 0
	s_mov_b32 m0, s64
	s_nop 0
	global_load_lds_dwordx4 v130, s[6:7]
	s_barrier
	s_waitcnt lgkmcnt(0)
	s_setprio 1
	v_mfma_f32_16x16x32_bf16 v[126:129], v[138:141], v[154:157], v[126:129]
	v_mfma_f32_16x16x32_bf16 v[126:129], v[142:145], v[158:161], v[126:129]
	v_mfma_f32_16x16x32_bf16 v[122:125], v[150:153], v[158:161], v[122:125]
	v_mfma_f32_16x16x32_bf16 v[122:125], v[146:149], v[154:157], v[122:125]
	v_mfma_f32_16x16x32_bf16 v[114:117], v[146:149], v[162:165], v[114:117]
	v_mfma_f32_16x16x32_bf16 v[114:117], v[150:153], v[166:169], v[114:117]
	v_mfma_f32_16x16x32_bf16 v[118:121], v[142:145], v[166:169], v[118:121]
	v_mfma_f32_16x16x32_bf16 v[118:121], v[138:141], v[162:165], v[118:121]
	v_mfma_f32_16x16x32_bf16 v[110:113], v[138:141], v[170:173], v[110:113]
	v_mfma_f32_16x16x32_bf16 v[110:113], v[142:145], v[174:177], v[110:113]
	v_mfma_f32_16x16x32_bf16 v[106:109], v[150:153], v[174:177], v[106:109]
	v_mfma_f32_16x16x32_bf16 v[106:109], v[146:149], v[170:173], v[106:109]
	v_mfma_f32_16x16x32_bf16 v[98:101], v[146:149], v[178:181], v[98:101]
	v_mfma_f32_16x16x32_bf16 v[98:101], v[150:153], v[182:185], v[98:101]
	v_mfma_f32_16x16x32_bf16 v[102:105], v[142:145], v[182:185], v[102:105]
	v_mfma_f32_16x16x32_bf16 v[102:105], v[138:141], v[178:181], v[102:105]
	s_setprio 0
	s_barrier
	ds_read_b128 v[186:189], v137 offset:16384
	ds_read_b128 v[196:199], v137 offset:17408
	ds_read_b128 v[212:215], v137 offset:18432
	ds_read_b128 v[220:223], v137 offset:19456
	s_barrier
	s_waitcnt lgkmcnt(0)
	s_setprio 1
	v_mfma_f32_16x16x32_bf16 v[94:97], v[186:189], v[154:157], v[94:97]
	v_mfma_f32_16x16x32_bf16 v[94:97], v[196:199], v[158:161], v[94:97]
	v_mfma_f32_16x16x32_bf16 v[90:93], v[220:223], v[158:161], v[90:93]
	v_mfma_f32_16x16x32_bf16 v[90:93], v[212:215], v[154:157], v[90:93]
	v_mfma_f32_16x16x32_bf16 v[82:85], v[212:215], v[162:165], v[82:85]
	v_mfma_f32_16x16x32_bf16 v[82:85], v[220:223], v[166:169], v[82:85]
	v_mfma_f32_16x16x32_bf16 v[86:89], v[196:199], v[166:169], v[86:89]
	v_mfma_f32_16x16x32_bf16 v[86:89], v[186:189], v[162:165], v[86:89]
	v_mfma_f32_16x16x32_bf16 v[78:81], v[186:189], v[170:173], v[78:81]
	v_mfma_f32_16x16x32_bf16 v[78:81], v[196:199], v[174:177], v[78:81]
	v_mfma_f32_16x16x32_bf16 v[74:77], v[220:223], v[174:177], v[74:77]
	v_mfma_f32_16x16x32_bf16 v[74:77], v[212:215], v[170:173], v[74:77]
	v_mfma_f32_16x16x32_bf16 v[66:69], v[212:215], v[178:181], v[66:69]
	v_mfma_f32_16x16x32_bf16 v[66:69], v[220:223], v[182:185], v[66:69]
	v_mfma_f32_16x16x32_bf16 v[70:73], v[196:199], v[182:185], v[70:73]
	v_mfma_f32_16x16x32_bf16 v[70:73], v[186:189], v[178:181], v[70:73]
	s_setprio 0
	s_barrier
; #define WAIT_V(n) asm volatile("s_waitcnt vmcnt(" #n ")" ::: "memory")
; #define WAIT_L(n) asm volatile("s_waitcnt lgkmcnt(" #n ")" ::: "memory")
; #define BAR __builtin_amdgcn_s_barrier()
; #define LDA(dst, b, h)                                                                                   \
;   _Pragma("unroll") for (int m = 0; m < 4; ++m) _Pragma("unroll") for (int k = 0; k < 2; ++k) dst[m][k] = \
;       *reinterpret_cast<const bf16x8*>(aRd + ((b) * 2 + (h)) * 16384 + m * 2048 + k * 1024)
; #define LDB(dst, b, h)                                                                                   \
;   _Pragma("unroll") for (int n = 0; n < 2; ++n) _Pragma("unroll") for (int k = 0; k < 2; ++k) dst[n][k] = \
;       *reinterpret_cast<const bf16x8*>(bRd + ((b) * 2 + (h)) * 16384 + n * 2048 + k * 1024)
; template <int EPI> ...
;     ...
;     LDA(At, 0, 1);
;     WAIT_V(4);
;     BAR;
;     WAIT_L(0);
;     MMA(1, 0, At, B0);
;     MMA(1, 1, At, B1);
;     BAR;
;   }
;   {
;     LDB(B0, 1, 0);
;     LDA(At, 1, 0);
;     WAIT_V(2);
;     BAR;
;     WAIT_L(0);
;     MMA(0, 0, At, B0);
	ds_read_b128 v[154:157], v136 offset:16384
	ds_read_b128 v[158:161], v136 offset:17408
	ds_read_b128 v[162:165], v136 offset:18432
	ds_read_b128 v[166:169], v136 offset:19456
	ds_read_b128 v[170:173], v136 offset:20480
	ds_read_b128 v[174:177], v136 offset:21504
	ds_read_b128 v[178:181], v136 offset:22528
	ds_read_b128 v[182:185], v136 offset:23552
	s_waitcnt vmcnt(4)
	s_barrier
	s_waitcnt lgkmcnt(0)
	s_setprio 1
	v_mfma_f32_16x16x32_bf16 v[62:65], v[138:141], v[154:157], v[62:65]
	v_mfma_f32_16x16x32_bf16 v[62:65], v[142:145], v[158:161], v[62:65]
	v_mfma_f32_16x16x32_bf16 v[58:61], v[150:153], v[158:161], v[58:61]
	v_mfma_f32_16x16x32_bf16 v[58:61], v[146:149], v[154:157], v[58:61]
	v_mfma_f32_16x16x32_bf16 v[50:53], v[146:149], v[162:165], v[50:53]
	v_mfma_f32_16x16x32_bf16 v[50:53], v[150:153], v[166:169], v[50:53]
	v_mfma_f32_16x16x32_bf16 v[54:57], v[142:145], v[166:169], v[54:57]
	v_mfma_f32_16x16x32_bf16 v[54:57], v[138:141], v[162:165], v[54:57]
	v_mfma_f32_16x16x32_bf16 v[46:49], v[138:141], v[170:173], v[46:49]
	v_mfma_f32_16x16x32_bf16 v[46:49], v[142:145], v[174:177], v[46:49]
	v_mfma_f32_16x16x32_bf16 v[42:45], v[150:153], v[174:177], v[42:45]
	v_mfma_f32_16x16x32_bf16 v[42:45], v[146:149], v[170:173], v[42:45]
	v_mfma_f32_16x16x32_bf16 v[34:37], v[146:149], v[178:181], v[34:37]
	v_mfma_f32_16x16x32_bf16 v[34:37], v[150:153], v[182:185], v[34:37]
	v_mfma_f32_16x16x32_bf16 v[38:41], v[142:145], v[182:185], v[38:41]
	v_mfma_f32_16x16x32_bf16 v[38:41], v[138:141], v[178:181], v[38:41]
	s_setprio 0
	s_setprio 1
	v_mfma_f32_16x16x32_bf16 v[30:33], v[186:189], v[154:157], v[30:33]
	v_mfma_f32_16x16x32_bf16 v[30:33], v[196:199], v[158:161], v[30:33]
	v_mfma_f32_16x16x32_bf16 v[26:29], v[220:223], v[158:161], v[26:29]
	v_mfma_f32_16x16x32_bf16 v[26:29], v[212:215], v[154:157], v[26:29]
	v_mfma_f32_16x16x32_bf16 v[18:21], v[212:215], v[162:165], v[18:21]
	v_mfma_f32_16x16x32_bf16 v[18:21], v[220:223], v[166:169], v[18:21]
	v_mfma_f32_16x16x32_bf16 v[22:25], v[196:199], v[166:169], v[22:25]
	v_mfma_f32_16x16x32_bf16 v[22:25], v[186:189], v[162:165], v[22:25]
	v_mfma_f32_16x16x32_bf16 v[14:17], v[186:189], v[170:173], v[14:17]
	v_mfma_f32_16x16x32_bf16 v[14:17], v[196:199], v[174:177], v[14:17]
	v_mfma_f32_16x16x32_bf16 v[10:13], v[220:223], v[174:177], v[10:13]
	v_mfma_f32_16x16x32_bf16 v[10:13], v[212:215], v[170:173], v[10:13]
	v_mfma_f32_16x16x32_bf16 v[2:5], v[212:215], v[178:181], v[2:5]
	v_mfma_f32_16x16x32_bf16 v[2:5], v[220:223], v[182:185], v[2:5]
	v_mfma_f32_16x16x32_bf16 v[6:9], v[196:199], v[182:185], v[6:9]
	v_mfma_f32_16x16x32_bf16 v[6:9], v[186:189], v[178:181], v[6:9]
	s_setprio 0
	s_barrier
	ds_read_b128 v[138:141], v137 offset:32768
	ds_read_b128 v[142:145], v137 offset:33792
	ds_read_b128 v[146:149], v137 offset:34816
	ds_read_b128 v[150:153], v137 offset:35840
	ds_read_b128 v[154:157], v136 offset:32768
	ds_read_b128 v[158:161], v136 offset:33792
	ds_read_b128 v[162:165], v136 offset:34816
	ds_read_b128 v[166:169], v136 offset:35840
	ds_read_b128 v[170:173], v136 offset:36864
	ds_read_b128 v[174:177], v136 offset:37888
	ds_read_b128 v[178:181], v136 offset:38912
	ds_read_b128 v[182:185], v136 offset:39936
	s_waitcnt vmcnt(2)
	s_barrier
	s_waitcnt lgkmcnt(0)
	s_setprio 1
	v_mfma_f32_16x16x32_bf16 v[126:129], v[138:141], v[154:157], v[126:129]
	v_mfma_f32_16x16x32_bf16 v[126:129], v[142:145], v[158:161], v[126:129]
	v_mfma_f32_16x16x32_bf16 v[122:125], v[150:153], v[158:161], v[122:125]
	v_mfma_f32_16x16x32_bf16 v[122:125], v[146:149], v[154:157], v[122:125]
	v_mfma_f32_16x16x32_bf16 v[114:117], v[146:149], v[162:165], v[114:117]
	v_mfma_f32_16x16x32_bf16 v[114:117], v[150:153], v[166:169], v[114:117]
	v_mfma_f32_16x16x32_bf16 v[118:121], v[142:145], v[166:169], v[118:121]
	v_mfma_f32_16x16x32_bf16 v[118:121], v[138:141], v[162:165], v[118:121]
	v_mfma_f32_16x16x32_bf16 v[110:113], v[138:141], v[170:173], v[110:113]
	v_mfma_f32_16x16x32_bf16 v[110:113], v[142:145], v[174:177], v[110:113]
	v_mfma_f32_16x16x32_bf16 v[106:109], v[150:153], v[174:177], v[106:109]
	v_mfma_f32_16x16x32_bf16 v[106:109], v[146:149], v[170:173], v[106:109]
	v_mfma_f32_16x16x32_bf16 v[98:101], v[146:149], v[178:181], v[98:101]
	v_mfma_f32_16x16x32_bf16 v[98:101], v[150:153], v[182:185], v[98:101]
	v_mfma_f32_16x16x32_bf16 v[102:105], v[142:145], v[182:185], v[102:105]
	v_mfma_f32_16x16x32_bf16 v[102:105], v[138:141], v[178:181], v[102:105]
	s_setprio 0
	s_barrier
; #define WAIT_V(n) asm volatile("s_waitcnt vmcnt(" #n ")" ::: "memory")
; #define WAIT_L(n) asm volatile("s_waitcnt lgkmcnt(" #n ")" ::: "memory")
; #define BAR __builtin_amdgcn_s_barrier()
; #define LDA(dst, b, h)                                                                                   \
;   _Pragma("unroll") for (int m = 0; m < 4; ++m) _Pragma("unroll") for (int k = 0; k < 2; ++k) dst[m][k] = \
;       *reinterpret_cast<const bf16x8*>(aRd + ((b) * 2 + (h)) * 16384 + m * 2048 + k * 1024)
; #define LDB(dst, b, h)                                                                                   \
;   _Pragma("unroll") for (int n = 0; n < 2; ++n) _Pragma("unroll") for (int k = 0; k < 2; ++k) dst[n][k] = \
;       *reinterpret_cast<const bf16x8*>(bRd + ((b) * 2 + (h)) * 16384 + n * 2048 + k * 1024)
; template <int EPI> ...
;     ...
;     LDB(B1, 1, 1);
;     WAIT_V(0);
;     BAR;
;     WAIT_L(0);
;     MMA(0, 1, At, B1);
;     BAR;
;     LDA(At, 1, 1);
;     BAR;
;     WAIT_L(0);
;     MMA(1, 0, At, B0);
;     MMA(1, 1, At, B1);
;     BAR;
;   }
;   if (wr == 0) BAR;
	ds_read_b128 v[186:189], v137 offset:49152
	ds_read_b128 v[196:199], v137 offset:50176
	ds_read_b128 v[212:215], v137 offset:51200
	ds_read_b128 v[220:223], v137 offset:52224
	s_waitcnt vmcnt(0)
	s_barrier
	s_waitcnt lgkmcnt(0)
	s_setprio 1
	v_mfma_f32_16x16x32_bf16 v[94:97], v[186:189], v[154:157], v[94:97]
	v_mfma_f32_16x16x32_bf16 v[94:97], v[196:199], v[158:161], v[94:97]
	v_mfma_f32_16x16x32_bf16 v[90:93], v[220:223], v[158:161], v[90:93]
	v_mfma_f32_16x16x32_bf16 v[90:93], v[212:215], v[154:157], v[90:93]
	v_mfma_f32_16x16x32_bf16 v[82:85], v[212:215], v[162:165], v[82:85]
	v_mfma_f32_16x16x32_bf16 v[82:85], v[220:223], v[166:169], v[82:85]
	v_mfma_f32_16x16x32_bf16 v[86:89], v[196:199], v[166:169], v[86:89]
	v_mfma_f32_16x16x32_bf16 v[86:89], v[186:189], v[162:165], v[86:89]
	v_mfma_f32_16x16x32_bf16 v[78:81], v[186:189], v[170:173], v[78:81]
	v_mfma_f32_16x16x32_bf16 v[78:81], v[196:199], v[174:177], v[78:81]
	v_mfma_f32_16x16x32_bf16 v[74:77], v[220:223], v[174:177], v[74:77]
	v_mfma_f32_16x16x32_bf16 v[74:77], v[212:215], v[170:173], v[74:77]
	v_mfma_f32_16x16x32_bf16 v[66:69], v[212:215], v[178:181], v[66:69]
	v_mfma_f32_16x16x32_bf16 v[66:69], v[220:223], v[182:185], v[66:69]
	v_mfma_f32_16x16x32_bf16 v[70:73], v[196:199], v[182:185], v[70:73]
	v_mfma_f32_16x16x32_bf16 v[70:73], v[186:189], v[178:181], v[70:73]
	s_setprio 0
	s_barrier
	ds_read_b128 v[154:157], v136 offset:49152
	ds_read_b128 v[158:161], v136 offset:50176
	ds_read_b128 v[162:165], v136 offset:51200
	ds_read_b128 v[166:169], v136 offset:52224
	ds_read_b128 v[170:173], v136 offset:53248
	ds_read_b128 v[174:177], v136 offset:54272
	ds_read_b128 v[178:181], v136 offset:55296
	ds_read_b128 v[182:185], v136 offset:56320
	s_barrier
	s_waitcnt lgkmcnt(0)
	s_setprio 1
	v_mfma_f32_16x16x32_bf16 v[62:65], v[138:141], v[154:157], v[62:65]
	v_mfma_f32_16x16x32_bf16 v[62:65], v[142:145], v[158:161], v[62:65]
	v_mfma_f32_16x16x32_bf16 v[58:61], v[150:153], v[158:161], v[58:61]
	v_mfma_f32_16x16x32_bf16 v[58:61], v[146:149], v[154:157], v[58:61]
	v_mfma_f32_16x16x32_bf16 v[50:53], v[146:149], v[162:165], v[50:53]
	v_mfma_f32_16x16x32_bf16 v[50:53], v[150:153], v[166:169], v[50:53]
	v_mfma_f32_16x16x32_bf16 v[54:57], v[142:145], v[166:169], v[54:57]
	v_mfma_f32_16x16x32_bf16 v[54:57], v[138:141], v[162:165], v[54:57]
	v_mfma_f32_16x16x32_bf16 v[46:49], v[138:141], v[170:173], v[46:49]
	v_mfma_f32_16x16x32_bf16 v[46:49], v[142:145], v[174:177], v[46:49]
	v_mfma_f32_16x16x32_bf16 v[42:45], v[150:153], v[174:177], v[42:45]
	v_mfma_f32_16x16x32_bf16 v[42:45], v[146:149], v[170:173], v[42:45]
	v_mfma_f32_16x16x32_bf16 v[34:37], v[146:149], v[178:181], v[34:37]
	v_mfma_f32_16x16x32_bf16 v[34:37], v[150:153], v[182:185], v[34:37]
	v_mfma_f32_16x16x32_bf16 v[38:41], v[142:145], v[182:185], v[38:41]
	v_mfma_f32_16x16x32_bf16 v[38:41], v[138:141], v[178:181], v[38:41]
	s_setprio 0
	s_setprio 1
	v_mfma_f32_16x16x32_bf16 v[30:33], v[186:189], v[154:157], v[30:33]
	v_mfma_f32_16x16x32_bf16 v[30:33], v[196:199], v[158:161], v[30:33]
	v_mfma_f32_16x16x32_bf16 v[26:29], v[220:223], v[158:161], v[26:29]
	v_mfma_f32_16x16x32_bf16 v[26:29], v[212:215], v[154:157], v[26:29]
	v_mfma_f32_16x16x32_bf16 v[18:21], v[212:215], v[162:165], v[18:21]
	v_mfma_f32_16x16x32_bf16 v[18:21], v[220:223], v[166:169], v[18:21]
	v_mfma_f32_16x16x32_bf16 v[22:25], v[196:199], v[166:169], v[22:25]
	v_mfma_f32_16x16x32_bf16 v[22:25], v[186:189], v[162:165], v[22:25]
	v_mfma_f32_16x16x32_bf16 v[14:17], v[186:189], v[170:173], v[14:17]
	v_mfma_f32_16x16x32_bf16 v[14:17], v[196:199], v[174:177], v[14:17]
	v_mfma_f32_16x16x32_bf16 v[10:13], v[220:223], v[174:177], v[10:13]
	v_mfma_f32_16x16x32_bf16 v[10:13], v[212:215], v[170:173], v[10:13]
	v_mfma_f32_16x16x32_bf16 v[2:5], v[212:215], v[178:181], v[2:5]
	v_mfma_f32_16x16x32_bf16 v[2:5], v[220:223], v[182:185], v[2:5]
	v_mfma_f32_16x16x32_bf16 v[6:9], v[196:199], v[182:185], v[6:9]
	v_mfma_f32_16x16x32_bf16 v[6:9], v[186:189], v[178:181], v[6:9]
	s_setprio 0
	s_movk_i32 s6, 0x100
	v_cmp_gt_u32_e32 vcc, s6, v134
	s_barrier
	s_and_saveexec_b64 s[12:13], vcc
	s_cbranch_execz .LBB0_117
	s_barrier

; #define WAIT_V(n) asm volatile("s_waitcnt vmcnt(" #n ")" ::: "memory")
; #define WAIT_L(n) asm volatile("s_waitcnt lgkmcnt(" #n ")" ::: "memory")
; #define BAR __builtin_amdgcn_s_barrier()
; #define SCHED __builtin_amdgcn_sched_barrier(0)
; #define STAGE_A(b, h, kt)                                        \
;   do {                                                           \
;     const char* _g = Ab + (h) * halfK + (long)(kt) * 128;        \
;     GLDS2(_g, (unsigned)(((b) * 2 + (h)) * 16384));              \
;   } while (0)
; #define STAGE_B(b, h, kt)                                        \
;   do {                                                           \
;     const char* _g = Bb + (h) * halfK + (long)(kt) * 128;        \
;     GLDS2(_g, (unsigned)(65536 + ((b) * 2 + (h)) * 16384));      \
;   } while (0)
; #define LDA(dst, b, h)                                                                                   \
;   _Pragma("unroll") for (int m = 0; m < 4; ++m) _Pragma("unroll") for (int k = 0; k < 2; ++k) dst[m][k] = \
;       *reinterpret_cast<const bf16x8*>(aRd + ((b) * 2 + (h)) * 16384 + m * 2048 + k * 1024)
; #define LDB(dst, b, h)                                                                                   \
;   _Pragma("unroll") for (int n = 0; n < 2; ++n) _Pragma("unroll") for (int k = 0; k < 2; ++k) dst[n][k] = \
;       *reinterpret_cast<const bf16x8*>(bRd + ((b) * 2 + (h)) * 16384 + n * 2048 + k * 1024)
; template <int EPI> ...
;     ...
;     LDB(B0, 0, 0);
;     SCHED;
;     LDA(At, 0, 0);
;     STAGE_A(1, 1, t + 1);
;     WAIT_L(8);
;     BAR;
;     WAIT_L(0);
;     MMA(0, 0, At, B0);
;     BAR;
;     SCHED;
;     LDB(B1, 0, 1);
;     STAGE_B(0, 0, t + 2);
;     BAR;
;     WAIT_L(0);
;     MMA(0, 1, At, B1);
;     BAR;
;     LDA(At, 0, 1);
;     STAGE_A(0, 0, t + 2);
;     BAR;
;     WAIT_L(0);
;     MMA(1, 0, At, B0);
;     BAR;
;     SCHED;
;     STAGE_B(0, 1, t + 2);
;     WAIT_V(6);
;     BAR;
.LBB0_203:
	ds_read_b128 v[138:141], v137
	ds_read_b128 v[142:145], v137 offset:1024
	ds_read_b128 v[146:149], v137 offset:2048
	ds_read_b128 v[150:153], v137 offset:3072
	ds_read_b128 v[154:157], v136
	ds_read_b128 v[158:161], v136 offset:1024
	ds_read_b128 v[162:165], v136 offset:2048
	ds_read_b128 v[166:169], v136 offset:3072
	ds_read_b128 v[170:173], v136 offset:4096
	ds_read_b128 v[174:177], v136 offset:5120
	ds_read_b128 v[178:181], v136 offset:6144
	ds_read_b128 v[182:185], v136 offset:7168
	s_add_u32 s76, s6, s12
	s_addc_u32 s60, s7, s13
	s_add_u32 s74, s76, 0x80
	s_addc_u32 s75, s60, 0
	s_mov_b32 m0, vcc_lo
	s_nop 0
	global_load_lds_dwordx4 v132, s[74:75]
	s_nop 0
	s_mov_b32 m0, s92
	s_nop 0
	global_load_lds_dwordx4 v131, s[74:75]
	s_waitcnt lgkmcnt(8)
	s_barrier
	s_waitcnt lgkmcnt(0)
	s_setprio 1
	v_mfma_f32_16x16x32_bf16 v[126:129], v[138:141], v[154:157], v[126:129]
	v_mfma_f32_16x16x32_bf16 v[126:129], v[142:145], v[158:161], v[126:129]
	v_mfma_f32_16x16x32_bf16 v[122:125], v[150:153], v[158:161], v[122:125]
	v_mfma_f32_16x16x32_bf16 v[122:125], v[146:149], v[154:157], v[122:125]
	v_mfma_f32_16x16x32_bf16 v[114:117], v[146:149], v[162:165], v[114:117]
	v_mfma_f32_16x16x32_bf16 v[114:117], v[150:153], v[166:169], v[114:117]
	v_mfma_f32_16x16x32_bf16 v[118:121], v[142:145], v[166:169], v[118:121]
	v_mfma_f32_16x16x32_bf16 v[118:121], v[138:141], v[162:165], v[118:121]
	v_mfma_f32_16x16x32_bf16 v[110:113], v[138:141], v[170:173], v[110:113]
	v_mfma_f32_16x16x32_bf16 v[110:113], v[142:145], v[174:177], v[110:113]
	v_mfma_f32_16x16x32_bf16 v[106:109], v[150:153], v[174:177], v[106:109]
	v_mfma_f32_16x16x32_bf16 v[106:109], v[146:149], v[170:173], v[106:109]
	v_mfma_f32_16x16x32_bf16 v[98:101], v[146:149], v[178:181], v[98:101]
	v_mfma_f32_16x16x32_bf16 v[98:101], v[150:153], v[182:185], v[98:101]
	v_mfma_f32_16x16x32_bf16 v[102:105], v[142:145], v[182:185], v[102:105]
	v_mfma_f32_16x16x32_bf16 v[102:105], v[138:141], v[178:181], v[102:105]
	s_setprio 0
	s_barrier
	s_add_i32 s34, s34, 2
	ds_read_b128 v[186:189], v137 offset:16384
	ds_read_b128 v[220:223], v137 offset:17408
	ds_read_b128 v[224:227], v137 offset:18432
	ds_read_b128 v[228:231], v137 offset:19456
	s_add_u32 s49, s88, s12
	s_addc_u32 s22, s89, s13
	s_add_u32 s74, s49, 0x100
	s_addc_u32 s75, s22, 0
	s_mov_b32 m0, s20
	s_nop 0
	global_load_lds_dwordx4 v132, s[74:75]
	s_nop 0
	s_mov_b32 m0, s21
	s_nop 0
	global_load_lds_dwordx4 v131, s[74:75]
	s_barrier
	s_waitcnt lgkmcnt(0)
	s_setprio 1
	v_mfma_f32_16x16x32_bf16 v[94:97], v[186:189], v[154:157], v[94:97]
	v_mfma_f32_16x16x32_bf16 v[94:97], v[220:223], v[158:161], v[94:97]
	v_mfma_f32_16x16x32_bf16 v[90:93], v[228:231], v[158:161], v[90:93]
	v_mfma_f32_16x16x32_bf16 v[90:93], v[224:227], v[154:157], v[90:93]
	v_mfma_f32_16x16x32_bf16 v[82:85], v[224:227], v[162:165], v[82:85]
	v_mfma_f32_16x16x32_bf16 v[82:85], v[228:231], v[166:169], v[82:85]
	v_mfma_f32_16x16x32_bf16 v[86:89], v[220:223], v[166:169], v[86:89]
	v_mfma_f32_16x16x32_bf16 v[86:89], v[186:189], v[162:165], v[86:89]
	v_mfma_f32_16x16x32_bf16 v[78:81], v[186:189], v[170:173], v[78:81]
	v_mfma_f32_16x16x32_bf16 v[78:81], v[220:223], v[174:177], v[78:81]
	v_mfma_f32_16x16x32_bf16 v[74:77], v[228:231], v[174:177], v[74:77]
	v_mfma_f32_16x16x32_bf16 v[74:77], v[224:227], v[170:173], v[74:77]
	v_mfma_f32_16x16x32_bf16 v[66:69], v[224:227], v[178:181], v[66:69]
	v_mfma_f32_16x16x32_bf16 v[66:69], v[228:231], v[182:185], v[66:69]
	v_mfma_f32_16x16x32_bf16 v[70:73], v[220:223], v[182:185], v[70:73]
	v_mfma_f32_16x16x32_bf16 v[70:73], v[186:189], v[178:181], v[70:73]
	s_setprio 0
	s_barrier
	ds_read_b128 v[154:157], v136 offset:16384
	ds_read_b128 v[158:161], v136 offset:17408
	ds_read_b128 v[162:165], v136 offset:18432
	ds_read_b128 v[166:169], v136 offset:19456
	ds_read_b128 v[170:173], v136 offset:20480
	ds_read_b128 v[174:177], v136 offset:21504
	ds_read_b128 v[178:181], v136 offset:22528
	ds_read_b128 v[182:185], v136 offset:23552
	s_add_u32 s23, s90, s12
	s_addc_u32 s68, s91, s13
	s_add_u32 s74, s23, 0x100
	s_addc_u32 s75, s68, 0
	s_mov_b32 m0, s63
	s_nop 0
	global_load_lds_dwordx4 v132, s[74:75]
	s_nop 0
	s_mov_b32 m0, s78
	s_nop 0
	global_load_lds_dwordx4 v131, s[74:75]
	s_barrier
	s_waitcnt lgkmcnt(0)
	s_setprio 1
	v_mfma_f32_16x16x32_bf16 v[62:65], v[138:141], v[154:157], v[62:65]
	v_mfma_f32_16x16x32_bf16 v[62:65], v[142:145], v[158:161], v[62:65]
	v_mfma_f32_16x16x32_bf16 v[58:61], v[150:153], v[158:161], v[58:61]
	v_mfma_f32_16x16x32_bf16 v[58:61], v[146:149], v[154:157], v[58:61]
	v_mfma_f32_16x16x32_bf16 v[50:53], v[146:149], v[162:165], v[50:53]
	v_mfma_f32_16x16x32_bf16 v[50:53], v[150:153], v[166:169], v[50:53]
	v_mfma_f32_16x16x32_bf16 v[54:57], v[142:145], v[166:169], v[54:57]
	v_mfma_f32_16x16x32_bf16 v[54:57], v[138:141], v[162:165], v[54:57]
	v_mfma_f32_16x16x32_bf16 v[46:49], v[138:141], v[170:173], v[46:49]
	v_mfma_f32_16x16x32_bf16 v[46:49], v[142:145], v[174:177], v[46:49]
	v_mfma_f32_16x16x32_bf16 v[42:45], v[150:153], v[174:177], v[42:45]
	v_mfma_f32_16x16x32_bf16 v[42:45], v[146:149], v[170:173], v[42:45]
	v_mfma_f32_16x16x32_bf16 v[34:37], v[146:149], v[178:181], v[34:37]
	v_mfma_f32_16x16x32_bf16 v[34:37], v[150:153], v[182:185], v[34:37]
	v_mfma_f32_16x16x32_bf16 v[38:41], v[142:145], v[182:185], v[38:41]
	v_mfma_f32_16x16x32_bf16 v[38:41], v[138:141], v[178:181], v[38:41]
	s_setprio 0
	s_barrier
	s_add_u32 s69, s8, s12
	s_addc_u32 s54, s9, s13
	s_add_u32 s74, s69, 0x100
	s_addc_u32 s75, s54, 0
	s_mov_b32 m0, s79
	s_nop 0
	global_load_lds_dwordx4 v132, s[74:75]
	s_nop 0
	s_mov_b32 m0, s38
	s_nop 0
	global_load_lds_dwordx4 v131, s[74:75]
	s_waitcnt vmcnt(6)
	s_barrier
; #define WAIT_L(n) asm volatile("s_waitcnt lgkmcnt(" #n ")" ::: "memory")
; #define BAR __builtin_amdgcn_s_barrier()
; #define SCHED __builtin_amdgcn_sched_barrier(0)
; #define STAGE_A(b, h, kt)                                        \
;   do {                                                           \
;     const char* _g = Ab + (h) * halfK + (long)(kt) * 128;        \
;     GLDS2(_g, (unsigned)(((b) * 2 + (h)) * 16384));              \
;   } while (0)
; #define STAGE_B(b, h, kt)                                        \
;   do {                                                           \
;     const char* _g = Bb + (h) * halfK + (long)(kt) * 128;        \
;     GLDS2(_g, (unsigned)(65536 + ((b) * 2 + (h)) * 16384));      \
;   } while (0)
; #define LDA(dst, b, h)                                                                                   \
;   _Pragma("unroll") for (int m = 0; m < 4; ++m) _Pragma("unroll") for (int k = 0; k < 2; ++k) dst[m][k] = \
;       *reinterpret_cast<const bf16x8*>(aRd + ((b) * 2 + (h)) * 16384 + m * 2048 + k * 1024)
; #define LDB(dst, b, h)                                                                                   \
;   _Pragma("unroll") for (int n = 0; n < 2; ++n) _Pragma("unroll") for (int k = 0; k < 2; ++k) dst[n][k] = \
;       *reinterpret_cast<const bf16x8*>(bRd + ((b) * 2 + (h)) * 16384 + n * 2048 + k * 1024)
; template <int EPI> ...
;     ...
;     MMA(1, 1, At, B1);
;     BAR;
;     LDB(B0, 1, 0);
;     SCHED;
;     LDA(At, 1, 0);
;     STAGE_A(0, 1, t + 2);
;     WAIT_L(8);
;     BAR;
;     WAIT_L(0);
;     MMA(0, 0, At, B0);
;     BAR;
;     SCHED;
;     LDB(B1, 1, 1);
;     STAGE_B(1, 0, t + 3);
;     BAR;
;     WAIT_L(0);
;     MMA(0, 1, At, B1);
;     BAR;
;     LDA(At, 1, 1);
;     STAGE_A(1, 0, t + 3);
;     BAR;
	s_setprio 1
	v_mfma_f32_16x16x32_bf16 v[30:33], v[186:189], v[154:157], v[30:33]
	v_mfma_f32_16x16x32_bf16 v[30:33], v[220:223], v[158:161], v[30:33]
	v_mfma_f32_16x16x32_bf16 v[26:29], v[228:231], v[158:161], v[26:29]
	v_mfma_f32_16x16x32_bf16 v[26:29], v[224:227], v[154:157], v[26:29]
	v_mfma_f32_16x16x32_bf16 v[18:21], v[224:227], v[162:165], v[18:21]
	v_mfma_f32_16x16x32_bf16 v[18:21], v[228:231], v[166:169], v[18:21]
	v_mfma_f32_16x16x32_bf16 v[22:25], v[220:223], v[166:169], v[22:25]
	v_mfma_f32_16x16x32_bf16 v[22:25], v[186:189], v[162:165], v[22:25]
	v_mfma_f32_16x16x32_bf16 v[14:17], v[186:189], v[170:173], v[14:17]
	v_mfma_f32_16x16x32_bf16 v[14:17], v[220:223], v[174:177], v[14:17]
	v_mfma_f32_16x16x32_bf16 v[10:13], v[228:231], v[174:177], v[10:13]
	v_mfma_f32_16x16x32_bf16 v[10:13], v[224:227], v[170:173], v[10:13]
	v_mfma_f32_16x16x32_bf16 v[2:5], v[224:227], v[178:181], v[2:5]
	v_mfma_f32_16x16x32_bf16 v[2:5], v[228:231], v[182:185], v[2:5]
	v_mfma_f32_16x16x32_bf16 v[6:9], v[220:223], v[182:185], v[6:9]
	v_mfma_f32_16x16x32_bf16 v[6:9], v[186:189], v[178:181], v[6:9]
	s_setprio 0
	s_barrier
	ds_read_b128 v[138:141], v137 offset:32768
	ds_read_b128 v[142:145], v137 offset:33792
	ds_read_b128 v[146:149], v137 offset:34816
	ds_read_b128 v[150:153], v137 offset:35840
	ds_read_b128 v[154:157], v136 offset:32768
	ds_read_b128 v[158:161], v136 offset:33792
	ds_read_b128 v[162:165], v136 offset:34816
	ds_read_b128 v[166:169], v136 offset:35840
	ds_read_b128 v[170:173], v136 offset:36864
	ds_read_b128 v[174:177], v136 offset:37888
	ds_read_b128 v[178:181], v136 offset:38912
	ds_read_b128 v[182:185], v136 offset:39936
	s_add_u32 s74, s76, 0x100
	s_addc_u32 s75, s60, 0
	s_mov_b32 m0, s39
	s_nop 0
	global_load_lds_dwordx4 v132, s[74:75]
	s_nop 0
	s_mov_b32 m0, s28
	s_nop 0
	global_load_lds_dwordx4 v131, s[74:75]
	s_waitcnt lgkmcnt(8)
	s_barrier
	s_waitcnt lgkmcnt(0)
	s_setprio 1
	v_mfma_f32_16x16x32_bf16 v[126:129], v[138:141], v[154:157], v[126:129]
	v_mfma_f32_16x16x32_bf16 v[126:129], v[142:145], v[158:161], v[126:129]
	v_mfma_f32_16x16x32_bf16 v[122:125], v[150:153], v[158:161], v[122:125]
	v_mfma_f32_16x16x32_bf16 v[122:125], v[146:149], v[154:157], v[122:125]
	v_mfma_f32_16x16x32_bf16 v[114:117], v[146:149], v[162:165], v[114:117]
	v_mfma_f32_16x16x32_bf16 v[114:117], v[150:153], v[166:169], v[114:117]
	v_mfma_f32_16x16x32_bf16 v[118:121], v[142:145], v[166:169], v[118:121]
	v_mfma_f32_16x16x32_bf16 v[118:121], v[138:141], v[162:165], v[118:121]
	v_mfma_f32_16x16x32_bf16 v[110:113], v[138:141], v[170:173], v[110:113]
	v_mfma_f32_16x16x32_bf16 v[110:113], v[142:145], v[174:177], v[110:113]
	v_mfma_f32_16x16x32_bf16 v[106:109], v[150:153], v[174:177], v[106:109]
	v_mfma_f32_16x16x32_bf16 v[106:109], v[146:149], v[170:173], v[106:109]
	v_mfma_f32_16x16x32_bf16 v[98:101], v[146:149], v[178:181], v[98:101]
	v_mfma_f32_16x16x32_bf16 v[98:101], v[150:153], v[182:185], v[98:101]
	v_mfma_f32_16x16x32_bf16 v[102:105], v[142:145], v[182:185], v[102:105]
	v_mfma_f32_16x16x32_bf16 v[102:105], v[138:141], v[178:181], v[102:105]
	s_setprio 0
	s_barrier
	ds_read_b128 v[186:189], v137 offset:49152
	ds_read_b128 v[220:223], v137 offset:50176
	ds_read_b128 v[224:227], v137 offset:51200
	ds_read_b128 v[228:231], v137 offset:52224
	s_add_u32 s74, s49, 0x180
	s_addc_u32 s75, s22, 0
	s_mov_b32 m0, s50
	s_nop 0
	global_load_lds_dwordx4 v132, s[74:75]
	s_nop 0
	s_mov_b32 m0, s51
	s_nop 0
	global_load_lds_dwordx4 v131, s[74:75]
	s_barrier
	s_waitcnt lgkmcnt(0)
	s_setprio 1
	v_mfma_f32_16x16x32_bf16 v[94:97], v[186:189], v[154:157], v[94:97]
	v_mfma_f32_16x16x32_bf16 v[94:97], v[220:223], v[158:161], v[94:97]
	v_mfma_f32_16x16x32_bf16 v[90:93], v[228:231], v[158:161], v[90:93]
	v_mfma_f32_16x16x32_bf16 v[90:93], v[224:227], v[154:157], v[90:93]
	v_mfma_f32_16x16x32_bf16 v[82:85], v[224:227], v[162:165], v[82:85]
	v_mfma_f32_16x16x32_bf16 v[82:85], v[228:231], v[166:169], v[82:85]
	v_mfma_f32_16x16x32_bf16 v[86:89], v[220:223], v[166:169], v[86:89]
	v_mfma_f32_16x16x32_bf16 v[86:89], v[186:189], v[162:165], v[86:89]
	v_mfma_f32_16x16x32_bf16 v[78:81], v[186:189], v[170:173], v[78:81]
	v_mfma_f32_16x16x32_bf16 v[78:81], v[220:223], v[174:177], v[78:81]
	v_mfma_f32_16x16x32_bf16 v[74:77], v[228:231], v[174:177], v[74:77]
	v_mfma_f32_16x16x32_bf16 v[74:77], v[224:227], v[170:173], v[74:77]
	v_mfma_f32_16x16x32_bf16 v[66:69], v[224:227], v[178:181], v[66:69]
	v_mfma_f32_16x16x32_bf16 v[66:69], v[228:231], v[182:185], v[66:69]
	v_mfma_f32_16x16x32_bf16 v[70:73], v[220:223], v[182:185], v[70:73]
	v_mfma_f32_16x16x32_bf16 v[70:73], v[186:189], v[178:181], v[70:73]
	s_setprio 0
	s_barrier
	ds_read_b128 v[154:157], v136 offset:49152
	ds_read_b128 v[158:161], v136 offset:50176
	ds_read_b128 v[162:165], v136 offset:51200
	ds_read_b128 v[166:169], v136 offset:52224
	ds_read_b128 v[170:173], v136 offset:53248
	ds_read_b128 v[174:177], v136 offset:54272
	ds_read_b128 v[178:181], v136 offset:55296
	ds_read_b128 v[182:185], v136 offset:56320
	s_add_u32 s74, s23, 0x180
	s_addc_u32 s75, s68, 0
	s_mov_b32 m0, s93
	s_nop 0
	global_load_lds_dwordx4 v132, s[74:75]
	s_nop 0
	s_mov_b32 m0, vcc_hi
	s_nop 0
	global_load_lds_dwordx4 v131, s[74:75]
	s_barrier
; #define WAIT_V(n) asm volatile("s_waitcnt vmcnt(" #n ")" ::: "memory")
; #define WAIT_L(n) asm volatile("s_waitcnt lgkmcnt(" #n ")" ::: "memory")
; #define BAR __builtin_amdgcn_s_barrier()
; #define SCHED __builtin_amdgcn_sched_barrier(0)
; #define STAGE_A(b, h, kt)                                        \
;   do {                                                           \
;     const char* _g = Ab + (h) * halfK + (long)(kt) * 128;        \
;     GLDS2(_g, (unsigned)(((b) * 2 + (h)) * 16384));              \
;   } while (0)
; #define STAGE_B(b, h, kt)                                        \
;   do {                                                           \
;     const char* _g = Bb + (h) * halfK + (long)(kt) * 128;        \
;     GLDS2(_g, (unsigned)(65536 + ((b) * 2 + (h)) * 16384));      \
;   } while (0)
; #define LDA(dst, b, h)                                                                                   \
;   _Pragma("unroll") for (int m = 0; m < 4; ++m) _Pragma("unroll") for (int k = 0; k < 2; ++k) dst[m][k] = \
;       *reinterpret_cast<const bf16x8*>(aRd + ((b) * 2 + (h)) * 16384 + m * 2048 + k * 1024)
; #define LDB(dst, b, h)                                                                                   \
;   _Pragma("unroll") for (int n = 0; n < 2; ++n) _Pragma("unroll") for (int k = 0; k < 2; ++k) dst[n][k] = \
;       *reinterpret_cast<const bf16x8*>(bRd + ((b) * 2 + (h)) * 16384 + n * 2048 + k * 1024)
; template <int EPI> ...
;     ...
;     WAIT_L(0);
;     MMA(1, 0, At, B0);
;     BAR;
;     SCHED;
;     STAGE_B(1, 1, t + 3);
;     WAIT_V(6);
;     BAR;
;     MMA(1, 1, At, B1);
;     BAR;
;   }
;   {
;     LDB(B0, 0, 0);
;     LDA(At, 0, 0);
;     STAGE_A(1, 1, nt - 1);
;     BAR;
;     WAIT_L(0);
;     MMA(0, 0, At, B0);
;     BAR;
;     LDB(B1, 0, 1);
;     BAR;
;     WAIT_L(0);
;     MMA(0, 1, At, B1);
;     BAR;
	s_waitcnt lgkmcnt(0)
	s_setprio 1
	v_mfma_f32_16x16x32_bf16 v[62:65], v[138:141], v[154:157], v[62:65]
	v_mfma_f32_16x16x32_bf16 v[62:65], v[142:145], v[158:161], v[62:65]
	v_mfma_f32_16x16x32_bf16 v[58:61], v[150:153], v[158:161], v[58:61]
	v_mfma_f32_16x16x32_bf16 v[58:61], v[146:149], v[154:157], v[58:61]
	v_mfma_f32_16x16x32_bf16 v[50:53], v[146:149], v[162:165], v[50:53]
	v_mfma_f32_16x16x32_bf16 v[50:53], v[150:153], v[166:169], v[50:53]
	v_mfma_f32_16x16x32_bf16 v[54:57], v[142:145], v[166:169], v[54:57]
	v_mfma_f32_16x16x32_bf16 v[54:57], v[138:141], v[162:165], v[54:57]
	v_mfma_f32_16x16x32_bf16 v[46:49], v[138:141], v[170:173], v[46:49]
	v_mfma_f32_16x16x32_bf16 v[46:49], v[142:145], v[174:177], v[46:49]
	v_mfma_f32_16x16x32_bf16 v[42:45], v[150:153], v[174:177], v[42:45]
	v_mfma_f32_16x16x32_bf16 v[42:45], v[146:149], v[170:173], v[42:45]
	v_mfma_f32_16x16x32_bf16 v[34:37], v[146:149], v[178:181], v[34:37]
	v_mfma_f32_16x16x32_bf16 v[34:37], v[150:153], v[182:185], v[34:37]
	v_mfma_f32_16x16x32_bf16 v[38:41], v[142:145], v[182:185], v[38:41]
	v_mfma_f32_16x16x32_bf16 v[38:41], v[138:141], v[178:181], v[38:41]
	s_setprio 0
	s_barrier
	s_add_u32 s74, s69, 0x180
	s_addc_u32 s75, s54, 0
	s_mov_b32 m0, s10
	s_nop 0
	global_load_lds_dwordx4 v132, s[74:75]
	s_nop 0
	s_mov_b32 m0, s11
	s_nop 0
	global_load_lds_dwordx4 v131, s[74:75]
	s_waitcnt vmcnt(6)
	s_barrier
	s_setprio 1
	v_mfma_f32_16x16x32_bf16 v[30:33], v[186:189], v[154:157], v[30:33]
	v_mfma_f32_16x16x32_bf16 v[30:33], v[220:223], v[158:161], v[30:33]
	v_mfma_f32_16x16x32_bf16 v[26:29], v[228:231], v[158:161], v[26:29]
	v_mfma_f32_16x16x32_bf16 v[26:29], v[224:227], v[154:157], v[26:29]
	v_mfma_f32_16x16x32_bf16 v[18:21], v[224:227], v[162:165], v[18:21]
	v_mfma_f32_16x16x32_bf16 v[18:21], v[228:231], v[166:169], v[18:21]
	v_mfma_f32_16x16x32_bf16 v[22:25], v[220:223], v[166:169], v[22:25]
	v_mfma_f32_16x16x32_bf16 v[22:25], v[186:189], v[162:165], v[22:25]
	v_mfma_f32_16x16x32_bf16 v[14:17], v[186:189], v[170:173], v[14:17]
	v_mfma_f32_16x16x32_bf16 v[14:17], v[220:223], v[174:177], v[14:17]
	v_mfma_f32_16x16x32_bf16 v[10:13], v[228:231], v[174:177], v[10:13]
	v_mfma_f32_16x16x32_bf16 v[10:13], v[224:227], v[170:173], v[10:13]
	v_mfma_f32_16x16x32_bf16 v[2:5], v[224:227], v[178:181], v[2:5]
	v_mfma_f32_16x16x32_bf16 v[2:5], v[228:231], v[182:185], v[2:5]
	v_mfma_f32_16x16x32_bf16 v[6:9], v[220:223], v[182:185], v[6:9]
	v_mfma_f32_16x16x32_bf16 v[6:9], v[186:189], v[178:181], v[6:9]
	s_setprio 0
	s_add_u32 s12, s12, 0x100
	s_addc_u32 s13, s13, 0
	s_cmp_lt_i32 s34, s29
	s_barrier
	s_cbranch_scc1 .LBB0_203
	ds_read_b128 v[138:141], v137
	ds_read_b128 v[142:145], v137 offset:1024
	ds_read_b128 v[146:149], v137 offset:2048
	ds_read_b128 v[150:153], v137 offset:3072
	ds_read_b128 v[154:157], v136
	ds_read_b128 v[158:161], v136 offset:1024
	ds_read_b128 v[162:165], v136 offset:2048
	ds_read_b128 v[166:169], v136 offset:3072
	ds_read_b128 v[170:173], v136 offset:4096
	ds_read_b128 v[174:177], v136 offset:5120
	ds_read_b128 v[178:181], v136 offset:6144
	ds_read_b128 v[182:185], v136 offset:7168
	s_add_i32 s34, s37, -1
	s_lshl_b64 s[8:9], s[34:35], 7
	s_add_u32 s6, s6, s8
	s_addc_u32 s7, s7, s9
	s_mov_b32 m0, vcc_lo
	s_nop 0
	global_load_lds_dwordx4 v132, s[6:7]
	s_nop 0
	s_mov_b32 m0, s92
	s_nop 0
	global_load_lds_dwordx4 v131, s[6:7]
	s_barrier
	s_waitcnt lgkmcnt(0)
	s_setprio 1
	s_waitcnt lgkmcnt(7)
	v_mfma_f32_16x16x32_bf16 v[126:129], v[138:141], v[154:157], v[126:129]
	v_mfma_f32_16x16x32_bf16 v[122:125], v[146:149], v[154:157], v[122:125]
	s_waitcnt lgkmcnt(5)
	v_mfma_f32_16x16x32_bf16 v[118:121], v[138:141], v[162:165], v[118:121]
	v_mfma_f32_16x16x32_bf16 v[114:117], v[146:149], v[162:165], v[114:117]
	s_waitcnt lgkmcnt(3)
	v_mfma_f32_16x16x32_bf16 v[110:113], v[138:141], v[170:173], v[110:113]
	s_waitcnt lgkmcnt(1)
	v_mfma_f32_16x16x32_bf16 v[102:105], v[138:141], v[178:181], v[102:105]
	v_mfma_f32_16x16x32_bf16 v[98:101], v[146:149], v[178:181], v[98:101]
	v_mfma_f32_16x16x32_bf16 v[126:129], v[142:145], v[158:161], v[126:129]
	v_mfma_f32_16x16x32_bf16 v[122:125], v[150:153], v[158:161], v[122:125]
	v_mfma_f32_16x16x32_bf16 v[118:121], v[142:145], v[166:169], v[118:121]
	v_mfma_f32_16x16x32_bf16 v[114:117], v[150:153], v[166:169], v[114:117]
	v_mfma_f32_16x16x32_bf16 v[110:113], v[142:145], v[174:177], v[110:113]
	v_mfma_f32_16x16x32_bf16 v[106:109], v[146:149], v[170:173], v[106:109]
	s_waitcnt lgkmcnt(0)
	v_mfma_f32_16x16x32_bf16 v[102:105], v[142:145], v[182:185], v[102:105]
	v_mfma_f32_16x16x32_bf16 v[98:101], v[150:153], v[182:185], v[98:101]
	v_mfma_f32_16x16x32_bf16 v[186:189], v[150:153], v[174:177], v[106:109]
	s_setprio 0
	s_barrier
	s_nop 1
	ds_read_b128 v[106:109], v137 offset:16384
	ds_read_b128 v[220:223], v137 offset:17408
	ds_read_b128 v[224:227], v137 offset:18432
	ds_read_b128 v[228:231], v137 offset:19456
	s_barrier
	s_waitcnt lgkmcnt(0)
	s_setprio 1
	s_waitcnt lgkmcnt(1)
	v_mfma_f32_16x16x32_bf16 v[90:93], v[224:227], v[154:157], v[90:93]
	v_mfma_f32_16x16x32_bf16 v[86:89], v[106:109], v[162:165], v[86:89]
	v_mfma_f32_16x16x32_bf16 v[82:85], v[224:227], v[162:165], v[82:85]
	v_mfma_f32_16x16x32_bf16 v[78:81], v[106:109], v[170:173], v[78:81]
	v_mfma_f32_16x16x32_bf16 v[74:77], v[224:227], v[170:173], v[74:77]
	v_mfma_f32_16x16x32_bf16 v[66:69], v[224:227], v[178:181], v[66:69]
	v_mfma_f32_16x16x32_bf16 v[94:97], v[106:109], v[154:157], v[94:97]
	s_waitcnt lgkmcnt(0)
	v_mfma_f32_16x16x32_bf16 v[90:93], v[228:231], v[158:161], v[90:93]
	v_mfma_f32_16x16x32_bf16 v[86:89], v[220:223], v[166:169], v[86:89]
	v_mfma_f32_16x16x32_bf16 v[82:85], v[228:231], v[166:169], v[82:85]
	v_mfma_f32_16x16x32_bf16 v[78:81], v[220:223], v[174:177], v[78:81]
	v_mfma_f32_16x16x32_bf16 v[74:77], v[228:231], v[174:177], v[74:77]
	v_mfma_f32_16x16x32_bf16 v[70:73], v[106:109], v[178:181], v[70:73]
	v_mfma_f32_16x16x32_bf16 v[66:69], v[228:231], v[182:185], v[66:69]
	v_mfma_f32_16x16x32_bf16 v[232:235], v[220:223], v[158:161], v[94:97]
	v_mfma_f32_16x16x32_bf16 v[154:157], v[220:223], v[182:185], v[70:73]
	s_setprio 0
	s_barrier
; #define WAIT_V(n) asm volatile("s_waitcnt vmcnt(" #n ")" ::: "memory")
; #define WAIT_L(n) asm volatile("s_waitcnt lgkmcnt(" #n ")" ::: "memory")
; #define BAR __builtin_amdgcn_s_barrier()
; #define LDA(dst, b, h)                                                                                   \
;   _Pragma("unroll") for (int m = 0; m < 4; ++m) _Pragma("unroll") for (int k = 0; k < 2; ++k) dst[m][k] = \
;       *reinterpret_cast<const bf16x8*>(aRd + ((b) * 2 + (h)) * 16384 + m * 2048 + k * 1024)
; #define LDB(dst, b, h)                                                                                   \
;   _Pragma("unroll") for (int n = 0; n < 2; ++n) _Pragma("unroll") for (int k = 0; k < 2; ++k) dst[n][k] = \
;       *reinterpret_cast<const bf16x8*>(bRd + ((b) * 2 + (h)) * 16384 + n * 2048 + k * 1024)
; template <int EPI> ...
;     ...
;     LDA(At, 0, 1);
;     WAIT_V(4);
;     BAR;
;     WAIT_L(0);
;     MMA(1, 0, At, B0);
;     MMA(1, 1, At, B1);
;     BAR;
;   }
;   {
;     LDB(B0, 1, 0);
;     LDA(At, 1, 0);
;     WAIT_V(2);
;     BAR;
;     WAIT_L(0);
;     MMA(0, 0, At, B0);
	s_nop 2
	ds_read_b128 v[70:73], v136 offset:16384
	ds_read_b128 v[94:97], v136 offset:17408
	ds_read_b128 v[158:161], v136 offset:18432
	ds_read_b128 v[162:165], v136 offset:19456
	ds_read_b128 v[166:169], v136 offset:20480
	ds_read_b128 v[170:173], v136 offset:21504
	ds_read_b128 v[174:177], v136 offset:22528
	ds_read_b128 v[178:181], v136 offset:23552
	s_waitcnt vmcnt(4)
	s_barrier
	s_waitcnt lgkmcnt(0)
	s_setprio 1
	s_waitcnt lgkmcnt(7)
	v_mfma_f32_16x16x32_bf16 v[62:65], v[138:141], v[70:73], v[62:65]
	s_waitcnt lgkmcnt(5)
	v_mfma_f32_16x16x32_bf16 v[54:57], v[138:141], v[158:161], v[54:57]
	v_mfma_f32_16x16x32_bf16 v[50:53], v[146:149], v[158:161], v[50:53]
	s_waitcnt lgkmcnt(1)
	v_mfma_f32_16x16x32_bf16 v[38:41], v[138:141], v[174:177], v[38:41]
	v_mfma_f32_16x16x32_bf16 v[62:65], v[142:145], v[94:97], v[62:65]
	v_mfma_f32_16x16x32_bf16 v[58:61], v[146:149], v[70:73], v[58:61]
	v_mfma_f32_16x16x32_bf16 v[54:57], v[142:145], v[162:165], v[54:57]
	v_mfma_f32_16x16x32_bf16 v[50:53], v[150:153], v[162:165], v[50:53]
	v_mfma_f32_16x16x32_bf16 v[46:49], v[138:141], v[166:169], v[46:49]
	v_mfma_f32_16x16x32_bf16 v[42:45], v[146:149], v[166:169], v[42:45]
	s_waitcnt lgkmcnt(0)
	v_mfma_f32_16x16x32_bf16 v[38:41], v[142:145], v[178:181], v[38:41]
	v_mfma_f32_16x16x32_bf16 v[34:37], v[146:149], v[174:177], v[34:37]
	v_mfma_f32_16x16x32_bf16 v[182:185], v[150:153], v[94:97], v[58:61]
	v_mfma_f32_16x16x32_bf16 v[236:239], v[142:145], v[170:173], v[46:49]
	v_mfma_f32_16x16x32_bf16 v[240:243], v[150:153], v[170:173], v[42:45]
	v_mfma_f32_16x16x32_bf16 v[138:141], v[150:153], v[178:181], v[34:37]
	s_setprio 0
	s_setprio 1
	v_mfma_f32_16x16x32_bf16 v[30:33], v[106:109], v[70:73], v[30:33]
	v_mfma_f32_16x16x32_bf16 v[26:29], v[224:227], v[70:73], v[26:29]
	v_mfma_f32_16x16x32_bf16 v[22:25], v[106:109], v[158:161], v[22:25]
	v_mfma_f32_16x16x32_bf16 v[18:21], v[224:227], v[158:161], v[18:21]
	v_mfma_f32_16x16x32_bf16 v[14:17], v[106:109], v[166:169], v[14:17]
	v_mfma_f32_16x16x32_bf16 v[10:13], v[224:227], v[166:169], v[10:13]
	v_mfma_f32_16x16x32_bf16 v[6:9], v[106:109], v[174:177], v[6:9]
	v_mfma_f32_16x16x32_bf16 v[2:5], v[224:227], v[174:177], v[2:5]
	v_mfma_f32_16x16x32_bf16 v[142:145], v[220:223], v[94:97], v[30:33]
	v_mfma_f32_16x16x32_bf16 v[146:149], v[228:231], v[94:97], v[26:29]
	v_mfma_f32_16x16x32_bf16 v[150:153], v[220:223], v[162:165], v[22:25]
	v_mfma_f32_16x16x32_bf16 v[158:161], v[228:231], v[162:165], v[18:21]
	v_mfma_f32_16x16x32_bf16 v[162:165], v[220:223], v[170:173], v[14:17]
	v_mfma_f32_16x16x32_bf16 v[166:169], v[228:231], v[170:173], v[10:13]
	v_mfma_f32_16x16x32_bf16 v[170:173], v[220:223], v[178:181], v[6:9]
	v_mfma_f32_16x16x32_bf16 v[174:177], v[228:231], v[178:181], v[2:5]
	s_setprio 0
	s_barrier
	ds_read_b128 v[18:21], v137 offset:32768
	ds_read_b128 v[22:25], v137 offset:33792
	ds_read_b128 v[26:29], v137 offset:34816
	ds_read_b128 v[178:181], v137 offset:35840
	ds_read_b128 v[46:49], v136 offset:32768
	ds_read_b128 v[58:61], v136 offset:33792
	ds_read_b128 v[70:73], v136 offset:34816
	ds_read_b128 v[220:223], v136 offset:35840
	ds_read_b128 v[224:227], v136 offset:36864
	ds_read_b128 v[228:231], v136 offset:37888
	ds_read_b128 v[244:247], v136 offset:38912
	ds_read_b128 v[248:251], v136 offset:39936
	s_waitcnt vmcnt(2)
	s_barrier
	s_waitcnt lgkmcnt(0)
	s_setprio 1
	s_waitcnt lgkmcnt(7)
	v_mfma_f32_16x16x32_bf16 v[2:5], v[18:21], v[46:49], v[126:129]
	s_waitcnt lgkmcnt(6)
	v_mfma_f32_16x16x32_bf16 v[94:97], v[22:25], v[58:61], v[2:5]
	v_mfma_f32_16x16x32_bf16 v[2:5], v[26:29], v[46:49], v[122:125]
	v_mfma_f32_16x16x32_bf16 v[106:109], v[178:181], v[58:61], v[2:5]
	s_waitcnt lgkmcnt(5)
	v_mfma_f32_16x16x32_bf16 v[2:5], v[18:21], v[70:73], v[118:121]
	s_waitcnt lgkmcnt(4)
	v_mfma_f32_16x16x32_bf16 v[30:33], v[22:25], v[220:223], v[2:5]
	v_mfma_f32_16x16x32_bf16 v[2:5], v[26:29], v[70:73], v[114:117]
	v_mfma_f32_16x16x32_bf16 v[42:45], v[178:181], v[220:223], v[2:5]
	s_waitcnt lgkmcnt(3)
	v_mfma_f32_16x16x32_bf16 v[2:5], v[18:21], v[224:227], v[110:113]
	s_waitcnt lgkmcnt(2)
	v_mfma_f32_16x16x32_bf16 v[10:13], v[22:25], v[228:231], v[2:5]
	v_mfma_f32_16x16x32_bf16 v[2:5], v[26:29], v[224:227], v[186:189]
	v_mfma_f32_16x16x32_bf16 v[14:17], v[178:181], v[228:231], v[2:5]
	s_waitcnt lgkmcnt(1)
	v_mfma_f32_16x16x32_bf16 v[2:5], v[18:21], v[244:247], v[102:105]
	v_mfma_f32_16x16x32_bf16 v[6:9], v[26:29], v[244:247], v[98:101]
	s_waitcnt lgkmcnt(0)
	v_mfma_f32_16x16x32_bf16 v[2:5], v[22:25], v[248:251], v[2:5]
	v_mfma_f32_16x16x32_bf16 v[6:9], v[178:181], v[248:251], v[6:9]
	s_setprio 0
	s_barrier
; #define WAIT_V(n) asm volatile("s_waitcnt vmcnt(" #n ")" ::: "memory")
; #define WAIT_L(n) asm volatile("s_waitcnt lgkmcnt(" #n ")" ::: "memory")
; #define BAR __builtin_amdgcn_s_barrier()
; #define LDA(dst, b, h)                                                                                   \
;   _Pragma("unroll") for (int m = 0; m < 4; ++m) _Pragma("unroll") for (int k = 0; k < 2; ++k) dst[m][k] = \
;       *reinterpret_cast<const bf16x8*>(aRd + ((b) * 2 + (h)) * 16384 + m * 2048 + k * 1024)
; #define LDB(dst, b, h)                                                                                   \
;   _Pragma("unroll") for (int n = 0; n < 2; ++n) _Pragma("unroll") for (int k = 0; k < 2; ++k) dst[n][k] = \
;       *reinterpret_cast<const bf16x8*>(bRd + ((b) * 2 + (h)) * 16384 + n * 2048 + k * 1024)
; template <int EPI> ...
;     ...
;     LDB(B1, 1, 1);
;     WAIT_V(0);
;     BAR;
;     WAIT_L(0);
;     MMA(0, 1, At, B1);
;     BAR;
;     LDA(At, 1, 1);
;     BAR;
;     WAIT_L(0);
;     MMA(1, 0, At, B0);
;     MMA(1, 1, At, B1);
;     BAR;
;   }
;   if (wr == 0) BAR;
	ds_read_b128 v[102:105], v137 offset:49152
	ds_read_b128 v[186:189], v137 offset:50176
	ds_read_b128 v[196:199], v137 offset:51200
	ds_read_b128 v[212:215], v137 offset:52224
	s_waitcnt vmcnt(0)
	s_barrier
	s_waitcnt lgkmcnt(0)
	s_setprio 1
	s_waitcnt lgkmcnt(3)
	v_mfma_f32_16x16x32_bf16 v[34:37], v[102:105], v[46:49], v[232:235]
	s_waitcnt lgkmcnt(1)
	v_mfma_f32_16x16x32_bf16 v[46:49], v[196:199], v[46:49], v[90:93]
	v_mfma_f32_16x16x32_bf16 v[74:77], v[196:199], v[224:227], v[74:77]
	v_mfma_f32_16x16x32_bf16 v[34:37], v[186:189], v[58:61], v[34:37]
	s_waitcnt lgkmcnt(0)
	v_mfma_f32_16x16x32_bf16 v[46:49], v[212:215], v[58:61], v[46:49]
	v_mfma_f32_16x16x32_bf16 v[58:61], v[102:105], v[70:73], v[86:89]
	v_mfma_f32_16x16x32_bf16 v[70:73], v[196:199], v[70:73], v[82:85]
	v_mfma_f32_16x16x32_bf16 v[78:81], v[102:105], v[224:227], v[78:81]
	v_mfma_f32_16x16x32_bf16 v[86:89], v[212:215], v[228:231], v[74:77]
	v_mfma_f32_16x16x32_bf16 v[74:77], v[102:105], v[244:247], v[154:157]
	v_mfma_f32_16x16x32_bf16 v[66:69], v[196:199], v[244:247], v[66:69]
	v_mfma_f32_16x16x32_bf16 v[58:61], v[186:189], v[220:223], v[58:61]
	v_mfma_f32_16x16x32_bf16 v[70:73], v[212:215], v[220:223], v[70:73]
	v_mfma_f32_16x16x32_bf16 v[78:81], v[186:189], v[228:231], v[78:81]
	v_mfma_f32_16x16x32_bf16 v[98:101], v[186:189], v[248:251], v[74:77]
	v_mfma_f32_16x16x32_bf16 v[110:113], v[212:215], v[248:251], v[66:69]
	s_setprio 0
	s_barrier
	s_nop 0
	ds_read_b128 v[66:69], v136 offset:49152
	ds_read_b128 v[74:77], v136 offset:50176
	ds_read_b128 v[82:85], v136 offset:51200
	ds_read_b128 v[90:93], v136 offset:52224
	ds_read_b128 v[154:157], v136 offset:53248
	ds_read_b128 v[220:223], v136 offset:54272
	ds_read_b128 v[224:227], v136 offset:55296
	ds_read_b128 v[228:231], v136 offset:56320
	s_barrier
	s_waitcnt lgkmcnt(0)
	s_setprio 1
	s_waitcnt lgkmcnt(5)
	v_mfma_f32_16x16x32_bf16 v[50:53], v[26:29], v[82:85], v[50:53]
	v_mfma_f32_16x16x32_bf16 v[62:65], v[18:21], v[66:69], v[62:65]
	v_mfma_f32_16x16x32_bf16 v[54:57], v[18:21], v[82:85], v[54:57]
	s_waitcnt lgkmcnt(4)
	v_mfma_f32_16x16x32_bf16 v[118:121], v[178:181], v[90:93], v[50:53]
	s_waitcnt lgkmcnt(3)
	v_mfma_f32_16x16x32_bf16 v[50:53], v[18:21], v[154:157], v[236:239]
	s_waitcnt lgkmcnt(1)
	v_mfma_f32_16x16x32_bf16 v[18:21], v[18:21], v[224:227], v[38:41]
	v_mfma_f32_16x16x32_bf16 v[122:125], v[22:25], v[74:77], v[62:65]
	v_mfma_f32_16x16x32_bf16 v[62:65], v[26:29], v[66:69], v[182:185]
	v_mfma_f32_16x16x32_bf16 v[114:117], v[22:25], v[90:93], v[54:57]
	v_mfma_f32_16x16x32_bf16 v[50:53], v[22:25], v[220:223], v[50:53]
	v_mfma_f32_16x16x32_bf16 v[54:57], v[26:29], v[154:157], v[240:243]
	s_waitcnt lgkmcnt(0)
	v_mfma_f32_16x16x32_bf16 v[18:21], v[22:25], v[228:231], v[18:21]
	v_mfma_f32_16x16x32_bf16 v[22:25], v[26:29], v[224:227], v[138:141]
	v_mfma_f32_16x16x32_bf16 v[126:129], v[178:181], v[74:77], v[62:65]
	v_mfma_f32_16x16x32_bf16 v[62:65], v[178:181], v[220:223], v[54:57]
	v_mfma_f32_16x16x32_bf16 v[22:25], v[178:181], v[228:231], v[22:25]
	s_setprio 0
	s_setprio 1
	v_mfma_f32_16x16x32_bf16 v[26:29], v[102:105], v[66:69], v[142:145]
	v_mfma_f32_16x16x32_bf16 v[38:41], v[196:199], v[66:69], v[146:149]
	v_mfma_f32_16x16x32_bf16 v[54:57], v[102:105], v[82:85], v[150:153]
	v_mfma_f32_16x16x32_bf16 v[66:69], v[196:199], v[82:85], v[158:161]
	v_mfma_f32_16x16x32_bf16 v[26:29], v[186:189], v[74:77], v[26:29]
	v_mfma_f32_16x16x32_bf16 v[38:41], v[212:215], v[74:77], v[38:41]
	v_mfma_f32_16x16x32_bf16 v[54:57], v[186:189], v[90:93], v[54:57]
	v_mfma_f32_16x16x32_bf16 v[66:69], v[212:215], v[90:93], v[66:69]
	v_mfma_f32_16x16x32_bf16 v[74:77], v[102:105], v[154:157], v[162:165]
	v_mfma_f32_16x16x32_bf16 v[82:85], v[196:199], v[154:157], v[166:169]
	v_mfma_f32_16x16x32_bf16 v[90:93], v[102:105], v[224:227], v[170:173]
	v_mfma_f32_16x16x32_bf16 v[102:105], v[196:199], v[224:227], v[174:177]
	v_mfma_f32_16x16x32_bf16 v[74:77], v[186:189], v[220:223], v[74:77]
	v_mfma_f32_16x16x32_bf16 v[82:85], v[212:215], v[220:223], v[82:85]
	v_mfma_f32_16x16x32_bf16 v[90:93], v[186:189], v[228:231], v[90:93]
	v_mfma_f32_16x16x32_bf16 v[102:105], v[212:215], v[228:231], v[102:105]
	s_setprio 0
	s_movk_i32 s6, 0x100
	v_cmp_gt_u32_e32 vcc, s6, v133
	s_barrier
	s_and_saveexec_b64 s[12:13], vcc
	s_cbranch_execz .LBB0_206
	s_barrier

; #define WAIT_V(n) asm volatile("s_waitcnt vmcnt(" #n ")" ::: "memory")
; #define WAIT_L(n) asm volatile("s_waitcnt lgkmcnt(" #n ")" ::: "memory")
; #define BAR __builtin_amdgcn_s_barrier()
; #define SCHED __builtin_amdgcn_sched_barrier(0)
; #define STAGE_A(b, h, kt)                                        \
;   do {                                                           \
;     const char* _g = Ab + (h) * halfK + (long)(kt) * 128;        \
;     GLDS2(_g, (unsigned)(((b) * 2 + (h)) * 16384));              \
;   } while (0)
; #define STAGE_B(b, h, kt)                                        \
;   do {                                                           \
;     const char* _g = Bb + (h) * halfK + (long)(kt) * 128;        \
;     GLDS2(_g, (unsigned)(65536 + ((b) * 2 + (h)) * 16384));      \
;   } while (0)
; #define LDA(dst, b, h)                                                                                   \
;   _Pragma("unroll") for (int m = 0; m < 4; ++m) _Pragma("unroll") for (int k = 0; k < 2; ++k) dst[m][k] = \
;       *reinterpret_cast<const bf16x8*>(aRd + ((b) * 2 + (h)) * 16384 + m * 2048 + k * 1024)
; #define LDB(dst, b, h)                                                                                   \
;   _Pragma("unroll") for (int n = 0; n < 2; ++n) _Pragma("unroll") for (int k = 0; k < 2; ++k) dst[n][k] = \
;       *reinterpret_cast<const bf16x8*>(bRd + ((b) * 2 + (h)) * 16384 + n * 2048 + k * 1024)
; template <int EPI> ...
;     ...
;     LDB(B0, 0, 0);
;     SCHED;
;     LDA(At, 0, 0);
;     STAGE_A(1, 1, t + 1);
;     WAIT_L(8);
;     BAR;
;     WAIT_L(0);
;     MMA(0, 0, At, B0);
;     BAR;
;     SCHED;
;     LDB(B1, 0, 1);
;     STAGE_B(0, 0, t + 2);
;     BAR;
;     WAIT_L(0);
;     MMA(0, 1, At, B1);
;     BAR;
;     LDA(At, 0, 1);
;     STAGE_A(0, 0, t + 2);
;     BAR;
;     WAIT_L(0);
;     MMA(1, 0, At, B0);
;     BAR;
;     SCHED;
;     STAGE_B(0, 1, t + 2);
;     WAIT_V(6);
;     BAR;
.LBB0_415:
	ds_read_b128 v[138:141], v136
	ds_read_b128 v[142:145], v136 offset:1024
	ds_read_b128 v[146:149], v136 offset:2048
	ds_read_b128 v[150:153], v136 offset:3072
	ds_read_b128 v[154:157], v135
	ds_read_b128 v[158:161], v135 offset:1024
	ds_read_b128 v[162:165], v135 offset:2048
	ds_read_b128 v[170:173], v135 offset:3072
	ds_read_b128 v[174:177], v135 offset:4096
	ds_read_b128 v[178:181], v135 offset:5120
	ds_read_b128 v[182:185], v135 offset:6144
	ds_read_b128 v[186:189], v135 offset:7168
	s_add_u32 s64, s10, s12
	s_addc_u32 s78, s11, s13
	s_add_u32 s74, s64, 0x80
	s_addc_u32 s75, s78, 0
	s_mov_b32 m0, s62
	s_nop 0
	global_load_lds_dwordx4 v132, s[74:75]
	s_nop 0
	s_mov_b32 m0, s59
	s_nop 0
	global_load_lds_dwordx4 v131, s[74:75]
	s_waitcnt lgkmcnt(8)
	s_barrier
	s_waitcnt lgkmcnt(0)
	s_setprio 1
	v_mfma_f32_16x16x32_bf16 v[126:129], v[138:141], v[154:157], v[126:129]
	v_mfma_f32_16x16x32_bf16 v[126:129], v[142:145], v[158:161], v[126:129]
	v_mfma_f32_16x16x32_bf16 v[122:125], v[150:153], v[158:161], v[122:125]
	v_mfma_f32_16x16x32_bf16 v[122:125], v[146:149], v[154:157], v[122:125]
	v_mfma_f32_16x16x32_bf16 v[114:117], v[146:149], v[162:165], v[114:117]
	v_mfma_f32_16x16x32_bf16 v[114:117], v[150:153], v[170:173], v[114:117]
	v_mfma_f32_16x16x32_bf16 v[118:121], v[142:145], v[170:173], v[118:121]
	v_mfma_f32_16x16x32_bf16 v[118:121], v[138:141], v[162:165], v[118:121]
	v_mfma_f32_16x16x32_bf16 v[110:113], v[138:141], v[174:177], v[110:113]
	v_mfma_f32_16x16x32_bf16 v[110:113], v[142:145], v[178:181], v[110:113]
	v_mfma_f32_16x16x32_bf16 v[106:109], v[150:153], v[178:181], v[106:109]
	v_mfma_f32_16x16x32_bf16 v[106:109], v[146:149], v[174:177], v[106:109]
	v_mfma_f32_16x16x32_bf16 v[98:101], v[146:149], v[182:185], v[98:101]
	v_mfma_f32_16x16x32_bf16 v[98:101], v[150:153], v[186:189], v[98:101]
	v_mfma_f32_16x16x32_bf16 v[102:105], v[142:145], v[186:189], v[102:105]
	v_mfma_f32_16x16x32_bf16 v[102:105], v[138:141], v[182:185], v[102:105]
	s_setprio 0
	s_barrier
	ds_read_b128 v[220:223], v136 offset:16384
	ds_read_b128 v[224:227], v136 offset:17408
	ds_read_b128 v[228:231], v136 offset:18432
	ds_read_b128 v[232:235], v136 offset:19456
	s_add_u32 s79, s72, s12
	s_addc_u32 s80, s73, s13
	s_add_u32 s74, s79, 0x100
	s_addc_u32 s75, s80, 0
	s_mov_b32 m0, s15
	s_nop 0
	global_load_lds_dwordx4 v132, s[74:75]
	s_nop 0
	s_mov_b32 m0, s33
	s_nop 0
	global_load_lds_dwordx4 v131, s[74:75]
	s_barrier
	s_waitcnt lgkmcnt(0)
	s_setprio 1
	v_mfma_f32_16x16x32_bf16 v[94:97], v[220:223], v[154:157], v[94:97]
	v_mfma_f32_16x16x32_bf16 v[94:97], v[224:227], v[158:161], v[94:97]
	v_mfma_f32_16x16x32_bf16 v[90:93], v[232:235], v[158:161], v[90:93]
	v_mfma_f32_16x16x32_bf16 v[90:93], v[228:231], v[154:157], v[90:93]
	v_mfma_f32_16x16x32_bf16 v[82:85], v[228:231], v[162:165], v[82:85]
	v_mfma_f32_16x16x32_bf16 v[82:85], v[232:235], v[170:173], v[82:85]
	v_mfma_f32_16x16x32_bf16 v[86:89], v[224:227], v[170:173], v[86:89]
	v_mfma_f32_16x16x32_bf16 v[86:89], v[220:223], v[162:165], v[86:89]
	v_mfma_f32_16x16x32_bf16 v[78:81], v[220:223], v[174:177], v[78:81]
	v_mfma_f32_16x16x32_bf16 v[78:81], v[224:227], v[178:181], v[78:81]
	v_mfma_f32_16x16x32_bf16 v[74:77], v[232:235], v[178:181], v[74:77]
	v_mfma_f32_16x16x32_bf16 v[74:77], v[228:231], v[174:177], v[74:77]
	v_mfma_f32_16x16x32_bf16 v[66:69], v[228:231], v[182:185], v[66:69]
	v_mfma_f32_16x16x32_bf16 v[66:69], v[232:235], v[186:189], v[66:69]
	v_mfma_f32_16x16x32_bf16 v[70:73], v[224:227], v[186:189], v[70:73]
	v_mfma_f32_16x16x32_bf16 v[70:73], v[220:223], v[182:185], v[70:73]
	s_setprio 0
	s_barrier
	ds_read_b128 v[154:157], v135 offset:16384
	ds_read_b128 v[158:161], v135 offset:17408
	ds_read_b128 v[162:165], v135 offset:18432
	ds_read_b128 v[170:173], v135 offset:19456
	ds_read_b128 v[174:177], v135 offset:20480
	ds_read_b128 v[178:181], v135 offset:21504
	ds_read_b128 v[182:185], v135 offset:22528
	ds_read_b128 v[186:189], v135 offset:23552
	s_add_u32 s81, s18, s12
	s_addc_u32 s82, s19, s13
	s_add_u32 s74, s81, 0x100
	s_addc_u32 s75, s82, 0
	s_mov_b32 m0, s2
	s_nop 0
	global_load_lds_dwordx4 v132, s[74:75]
	s_nop 0
	s_mov_b32 m0, s41
	s_nop 0
	global_load_lds_dwordx4 v131, s[74:75]
	s_barrier
	s_waitcnt lgkmcnt(0)
	s_setprio 1
	v_mfma_f32_16x16x32_bf16 v[62:65], v[138:141], v[154:157], v[62:65]
	v_mfma_f32_16x16x32_bf16 v[62:65], v[142:145], v[158:161], v[62:65]
	v_mfma_f32_16x16x32_bf16 v[58:61], v[150:153], v[158:161], v[58:61]
	v_mfma_f32_16x16x32_bf16 v[58:61], v[146:149], v[154:157], v[58:61]
	v_mfma_f32_16x16x32_bf16 v[50:53], v[146:149], v[162:165], v[50:53]
	v_mfma_f32_16x16x32_bf16 v[50:53], v[150:153], v[170:173], v[50:53]
	v_mfma_f32_16x16x32_bf16 v[54:57], v[142:145], v[170:173], v[54:57]
	v_mfma_f32_16x16x32_bf16 v[54:57], v[138:141], v[162:165], v[54:57]
	v_mfma_f32_16x16x32_bf16 v[46:49], v[138:141], v[174:177], v[46:49]
	v_mfma_f32_16x16x32_bf16 v[46:49], v[142:145], v[178:181], v[46:49]
	v_mfma_f32_16x16x32_bf16 v[42:45], v[150:153], v[178:181], v[42:45]
	v_mfma_f32_16x16x32_bf16 v[42:45], v[146:149], v[174:177], v[42:45]
	v_mfma_f32_16x16x32_bf16 v[34:37], v[146:149], v[182:185], v[34:37]
	v_mfma_f32_16x16x32_bf16 v[34:37], v[150:153], v[186:189], v[34:37]
	v_mfma_f32_16x16x32_bf16 v[38:41], v[142:145], v[186:189], v[38:41]
	v_mfma_f32_16x16x32_bf16 v[38:41], v[138:141], v[182:185], v[38:41]
	s_setprio 0
	s_barrier
	s_add_u32 s83, s6, s12
	s_addc_u32 s84, s7, s13
	s_add_u32 s74, s83, 0x100
	s_addc_u32 s75, s84, 0
	s_mov_b32 m0, s38
	s_nop 0
	global_load_lds_dwordx4 v132, s[74:75]
	s_nop 0
	s_mov_b32 m0, s39
	s_nop 0
	global_load_lds_dwordx4 v131, s[74:75]
	s_waitcnt vmcnt(6)
	s_barrier
; #define WAIT_L(n) asm volatile("s_waitcnt lgkmcnt(" #n ")" ::: "memory")
; #define BAR __builtin_amdgcn_s_barrier()
; #define SCHED __builtin_amdgcn_sched_barrier(0)
; #define STAGE_A(b, h, kt)                                        \
;   do {                                                           \
;     const char* _g = Ab + (h) * halfK + (long)(kt) * 128;        \
;     GLDS2(_g, (unsigned)(((b) * 2 + (h)) * 16384));              \
;   } while (0)
; #define STAGE_B(b, h, kt)                                        \
;   do {                                                           \
;     const char* _g = Bb + (h) * halfK + (long)(kt) * 128;        \
;     GLDS2(_g, (unsigned)(65536 + ((b) * 2 + (h)) * 16384));      \
;   } while (0)
; #define LDA(dst, b, h)                                                                                   \
;   _Pragma("unroll") for (int m = 0; m < 4; ++m) _Pragma("unroll") for (int k = 0; k < 2; ++k) dst[m][k] = \
;       *reinterpret_cast<const bf16x8*>(aRd + ((b) * 2 + (h)) * 16384 + m * 2048 + k * 1024)
; #define LDB(dst, b, h)                                                                                   \
;   _Pragma("unroll") for (int n = 0; n < 2; ++n) _Pragma("unroll") for (int k = 0; k < 2; ++k) dst[n][k] = \
;       *reinterpret_cast<const bf16x8*>(bRd + ((b) * 2 + (h)) * 16384 + n * 2048 + k * 1024)
; template <int EPI> ...
;     ...
;     MMA(1, 1, At, B1);
;     BAR;
;     LDB(B0, 1, 0);
;     SCHED;
;     LDA(At, 1, 0);
;     STAGE_A(0, 1, t + 2);
;     WAIT_L(8);
;     BAR;
;     WAIT_L(0);
;     MMA(0, 0, At, B0);
;     BAR;
;     SCHED;
;     LDB(B1, 1, 1);
;     STAGE_B(1, 0, t + 3);
;     BAR;
;     WAIT_L(0);
;     MMA(0, 1, At, B1);
;     BAR;
;     LDA(At, 1, 1);
;     STAGE_A(1, 0, t + 3);
;     BAR;
	s_setprio 1
	v_mfma_f32_16x16x32_bf16 v[30:33], v[220:223], v[154:157], v[30:33]
	v_mfma_f32_16x16x32_bf16 v[30:33], v[224:227], v[158:161], v[30:33]
	v_mfma_f32_16x16x32_bf16 v[26:29], v[232:235], v[158:161], v[26:29]
	v_mfma_f32_16x16x32_bf16 v[26:29], v[228:231], v[154:157], v[26:29]
	v_mfma_f32_16x16x32_bf16 v[18:21], v[228:231], v[162:165], v[18:21]
	v_mfma_f32_16x16x32_bf16 v[18:21], v[232:235], v[170:173], v[18:21]
	v_mfma_f32_16x16x32_bf16 v[22:25], v[224:227], v[170:173], v[22:25]
	v_mfma_f32_16x16x32_bf16 v[22:25], v[220:223], v[162:165], v[22:25]
	v_mfma_f32_16x16x32_bf16 v[14:17], v[220:223], v[174:177], v[14:17]
	v_mfma_f32_16x16x32_bf16 v[14:17], v[224:227], v[178:181], v[14:17]
	v_mfma_f32_16x16x32_bf16 v[10:13], v[232:235], v[178:181], v[10:13]
	v_mfma_f32_16x16x32_bf16 v[10:13], v[228:231], v[174:177], v[10:13]
	v_mfma_f32_16x16x32_bf16 v[2:5], v[228:231], v[182:185], v[2:5]
	v_mfma_f32_16x16x32_bf16 v[2:5], v[232:235], v[186:189], v[2:5]
	v_mfma_f32_16x16x32_bf16 v[6:9], v[224:227], v[186:189], v[6:9]
	v_mfma_f32_16x16x32_bf16 v[6:9], v[220:223], v[182:185], v[6:9]
	s_setprio 0
	s_barrier
	ds_read_b128 v[138:141], v136 offset:32768
	ds_read_b128 v[142:145], v136 offset:33792
	ds_read_b128 v[146:149], v136 offset:34816
	ds_read_b128 v[150:153], v136 offset:35840
	ds_read_b128 v[154:157], v135 offset:32768
	ds_read_b128 v[158:161], v135 offset:33792
	ds_read_b128 v[162:165], v135 offset:34816
	ds_read_b128 v[170:173], v135 offset:35840
	ds_read_b128 v[174:177], v135 offset:36864
	ds_read_b128 v[178:181], v135 offset:37888
	ds_read_b128 v[182:185], v135 offset:38912
	ds_read_b128 v[186:189], v135 offset:39936
	s_add_u32 s74, s64, 0x100
	s_addc_u32 s75, s78, 0
	s_mov_b32 m0, s47
	s_nop 0
	global_load_lds_dwordx4 v132, s[74:75]
	s_nop 0
	s_mov_b32 m0, s48
	s_nop 0
	global_load_lds_dwordx4 v131, s[74:75]
	s_waitcnt lgkmcnt(8)
	s_barrier
	s_waitcnt lgkmcnt(0)
	s_setprio 1
	v_mfma_f32_16x16x32_bf16 v[126:129], v[138:141], v[154:157], v[126:129]
	v_mfma_f32_16x16x32_bf16 v[126:129], v[142:145], v[158:161], v[126:129]
	v_mfma_f32_16x16x32_bf16 v[122:125], v[150:153], v[158:161], v[122:125]
	v_mfma_f32_16x16x32_bf16 v[122:125], v[146:149], v[154:157], v[122:125]
	v_mfma_f32_16x16x32_bf16 v[114:117], v[146:149], v[162:165], v[114:117]
	v_mfma_f32_16x16x32_bf16 v[114:117], v[150:153], v[170:173], v[114:117]
	v_mfma_f32_16x16x32_bf16 v[118:121], v[142:145], v[170:173], v[118:121]
	v_mfma_f32_16x16x32_bf16 v[118:121], v[138:141], v[162:165], v[118:121]
	v_mfma_f32_16x16x32_bf16 v[110:113], v[138:141], v[174:177], v[110:113]
	v_mfma_f32_16x16x32_bf16 v[110:113], v[142:145], v[178:181], v[110:113]
	v_mfma_f32_16x16x32_bf16 v[106:109], v[150:153], v[178:181], v[106:109]
	v_mfma_f32_16x16x32_bf16 v[106:109], v[146:149], v[174:177], v[106:109]
	v_mfma_f32_16x16x32_bf16 v[98:101], v[146:149], v[182:185], v[98:101]
	v_mfma_f32_16x16x32_bf16 v[98:101], v[150:153], v[186:189], v[98:101]
	v_mfma_f32_16x16x32_bf16 v[102:105], v[142:145], v[186:189], v[102:105]
	v_mfma_f32_16x16x32_bf16 v[102:105], v[138:141], v[182:185], v[102:105]
	s_setprio 0
	s_barrier
	ds_read_b128 v[220:223], v136 offset:49152
	ds_read_b128 v[224:227], v136 offset:50176
	ds_read_b128 v[228:231], v136 offset:51200
	ds_read_b128 v[232:235], v136 offset:52224
	s_add_u32 s74, s79, 0x180
	s_addc_u32 s75, s80, 0
	s_mov_b32 m0, s50
	s_nop 0
	global_load_lds_dwordx4 v132, s[74:75]
	s_nop 0
	s_mov_b32 m0, s51
	s_nop 0
	global_load_lds_dwordx4 v131, s[74:75]
	s_barrier
	s_waitcnt lgkmcnt(0)
	s_setprio 1
	v_mfma_f32_16x16x32_bf16 v[94:97], v[220:223], v[154:157], v[94:97]
	v_mfma_f32_16x16x32_bf16 v[94:97], v[224:227], v[158:161], v[94:97]
	v_mfma_f32_16x16x32_bf16 v[90:93], v[232:235], v[158:161], v[90:93]
	v_mfma_f32_16x16x32_bf16 v[90:93], v[228:231], v[154:157], v[90:93]
	v_mfma_f32_16x16x32_bf16 v[82:85], v[228:231], v[162:165], v[82:85]
	v_mfma_f32_16x16x32_bf16 v[82:85], v[232:235], v[170:173], v[82:85]
	v_mfma_f32_16x16x32_bf16 v[86:89], v[224:227], v[170:173], v[86:89]
	v_mfma_f32_16x16x32_bf16 v[86:89], v[220:223], v[162:165], v[86:89]
	v_mfma_f32_16x16x32_bf16 v[78:81], v[220:223], v[174:177], v[78:81]
	v_mfma_f32_16x16x32_bf16 v[78:81], v[224:227], v[178:181], v[78:81]
	v_mfma_f32_16x16x32_bf16 v[74:77], v[232:235], v[178:181], v[74:77]
	v_mfma_f32_16x16x32_bf16 v[74:77], v[228:231], v[174:177], v[74:77]
	v_mfma_f32_16x16x32_bf16 v[66:69], v[228:231], v[182:185], v[66:69]
	v_mfma_f32_16x16x32_bf16 v[66:69], v[232:235], v[186:189], v[66:69]
	v_mfma_f32_16x16x32_bf16 v[70:73], v[224:227], v[186:189], v[70:73]
	v_mfma_f32_16x16x32_bf16 v[70:73], v[220:223], v[182:185], v[70:73]
	s_setprio 0
	s_barrier
	ds_read_b128 v[154:157], v135 offset:49152
	ds_read_b128 v[158:161], v135 offset:50176
	ds_read_b128 v[162:165], v135 offset:51200
	ds_read_b128 v[170:173], v135 offset:52224
	ds_read_b128 v[174:177], v135 offset:53248
	ds_read_b128 v[178:181], v135 offset:54272
	ds_read_b128 v[182:185], v135 offset:55296
	ds_read_b128 v[186:189], v135 offset:56320
	s_add_u32 s74, s81, 0x180
	s_addc_u32 s75, s82, 0
	s_mov_b32 m0, s58
	s_nop 0
	global_load_lds_dwordx4 v132, s[74:75]
	s_nop 0
	s_mov_b32 m0, s63
	s_nop 0
	global_load_lds_dwordx4 v131, s[74:75]
	s_barrier
; #define WAIT_V(n) asm volatile("s_waitcnt vmcnt(" #n ")" ::: "memory")
; #define WAIT_L(n) asm volatile("s_waitcnt lgkmcnt(" #n ")" ::: "memory")
; #define BAR __builtin_amdgcn_s_barrier()
; #define SCHED __builtin_amdgcn_sched_barrier(0)
; #define STAGE_A(b, h, kt)                                        \
;   do {                                                           \
;     const char* _g = Ab + (h) * halfK + (long)(kt) * 128;        \
;     GLDS2(_g, (unsigned)(((b) * 2 + (h)) * 16384));              \
;   } while (0)
; #define STAGE_B(b, h, kt)                                        \
;   do {                                                           \
;     const char* _g = Bb + (h) * halfK + (long)(kt) * 128;        \
;     GLDS2(_g, (unsigned)(65536 + ((b) * 2 + (h)) * 16384));      \
;   } while (0)
; #define LDA(dst, b, h)                                                                                   \
;   _Pragma("unroll") for (int m = 0; m < 4; ++m) _Pragma("unroll") for (int k = 0; k < 2; ++k) dst[m][k] = \
;       *reinterpret_cast<const bf16x8*>(aRd + ((b) * 2 + (h)) * 16384 + m * 2048 + k * 1024)
; #define LDB(dst, b, h)                                                                                   \
;   _Pragma("unroll") for (int n = 0; n < 2; ++n) _Pragma("unroll") for (int k = 0; k < 2; ++k) dst[n][k] = \
;       *reinterpret_cast<const bf16x8*>(bRd + ((b) * 2 + (h)) * 16384 + n * 2048 + k * 1024)
; template <int EPI> ...
;     ...
;     WAIT_L(0);
;     MMA(1, 0, At, B0);
;     BAR;
;     SCHED;
;     STAGE_B(1, 1, t + 3);
;     WAIT_V(6);
;     BAR;
;     MMA(1, 1, At, B1);
;     BAR;
;   }
;   {
;     LDB(B0, 0, 0);
;     LDA(At, 0, 0);
;     STAGE_A(1, 1, nt - 1);
;     BAR;
;     WAIT_L(0);
;     MMA(0, 0, At, B0);
;     BAR;
;     LDB(B1, 0, 1);
;     BAR;
;     WAIT_L(0);
;     MMA(0, 1, At, B1);
;     BAR;
	s_waitcnt lgkmcnt(0)
	s_setprio 1
	v_mfma_f32_16x16x32_bf16 v[62:65], v[138:141], v[154:157], v[62:65]
	v_mfma_f32_16x16x32_bf16 v[62:65], v[142:145], v[158:161], v[62:65]
	v_mfma_f32_16x16x32_bf16 v[58:61], v[150:153], v[158:161], v[58:61]
	v_mfma_f32_16x16x32_bf16 v[58:61], v[146:149], v[154:157], v[58:61]
	v_mfma_f32_16x16x32_bf16 v[50:53], v[146:149], v[162:165], v[50:53]
	v_mfma_f32_16x16x32_bf16 v[50:53], v[150:153], v[170:173], v[50:53]
	v_mfma_f32_16x16x32_bf16 v[54:57], v[142:145], v[170:173], v[54:57]
	v_mfma_f32_16x16x32_bf16 v[54:57], v[138:141], v[162:165], v[54:57]
	v_mfma_f32_16x16x32_bf16 v[46:49], v[138:141], v[174:177], v[46:49]
	v_mfma_f32_16x16x32_bf16 v[46:49], v[142:145], v[178:181], v[46:49]
	v_mfma_f32_16x16x32_bf16 v[42:45], v[150:153], v[178:181], v[42:45]
	v_mfma_f32_16x16x32_bf16 v[42:45], v[146:149], v[174:177], v[42:45]
	v_mfma_f32_16x16x32_bf16 v[34:37], v[146:149], v[182:185], v[34:37]
	v_mfma_f32_16x16x32_bf16 v[34:37], v[150:153], v[186:189], v[34:37]
	v_mfma_f32_16x16x32_bf16 v[38:41], v[142:145], v[186:189], v[38:41]
	v_mfma_f32_16x16x32_bf16 v[38:41], v[138:141], v[182:185], v[38:41]
	s_setprio 0
	s_barrier
	s_add_u32 s74, s83, 0x180
	s_addc_u32 s75, s84, 0
	s_mov_b32 m0, s8
	s_nop 0
	global_load_lds_dwordx4 v132, s[74:75]
	s_nop 0
	s_mov_b32 m0, s9
	s_nop 0
	global_load_lds_dwordx4 v131, s[74:75]
	s_waitcnt vmcnt(6)
	s_barrier
	s_setprio 1
	v_mfma_f32_16x16x32_bf16 v[30:33], v[220:223], v[154:157], v[30:33]
	v_mfma_f32_16x16x32_bf16 v[30:33], v[224:227], v[158:161], v[30:33]
	v_mfma_f32_16x16x32_bf16 v[26:29], v[232:235], v[158:161], v[26:29]
	v_mfma_f32_16x16x32_bf16 v[26:29], v[228:231], v[154:157], v[26:29]
	v_mfma_f32_16x16x32_bf16 v[18:21], v[228:231], v[162:165], v[18:21]
	v_mfma_f32_16x16x32_bf16 v[18:21], v[232:235], v[170:173], v[18:21]
	v_mfma_f32_16x16x32_bf16 v[22:25], v[224:227], v[170:173], v[22:25]
	v_mfma_f32_16x16x32_bf16 v[22:25], v[220:223], v[162:165], v[22:25]
	v_mfma_f32_16x16x32_bf16 v[14:17], v[220:223], v[174:177], v[14:17]
	v_mfma_f32_16x16x32_bf16 v[14:17], v[224:227], v[178:181], v[14:17]
	v_mfma_f32_16x16x32_bf16 v[10:13], v[232:235], v[178:181], v[10:13]
	v_mfma_f32_16x16x32_bf16 v[10:13], v[228:231], v[174:177], v[10:13]
	v_mfma_f32_16x16x32_bf16 v[2:5], v[228:231], v[182:185], v[2:5]
	v_mfma_f32_16x16x32_bf16 v[2:5], v[232:235], v[186:189], v[2:5]
	v_mfma_f32_16x16x32_bf16 v[6:9], v[224:227], v[186:189], v[6:9]
	v_mfma_f32_16x16x32_bf16 v[6:9], v[220:223], v[182:185], v[6:9]
	s_setprio 0
	s_add_i32 s37, s37, 2
	s_add_u32 s12, s12, 0x100
	s_addc_u32 s13, s13, 0
	s_cmp_lt_u32 s37, 28
	s_barrier
	s_cbranch_scc1 .LBB0_415
	ds_read_b128 v[138:141], v136
	ds_read_b128 v[142:145], v136 offset:1024
	ds_read_b128 v[146:149], v136 offset:2048
	ds_read_b128 v[150:153], v136 offset:3072
	ds_read_b128 v[154:157], v135
	ds_read_b128 v[158:161], v135 offset:1024
	ds_read_b128 v[162:165], v135 offset:2048
	ds_read_b128 v[170:173], v135 offset:3072
	ds_read_b128 v[174:177], v135 offset:4096
	ds_read_b128 v[178:181], v135 offset:5120
	ds_read_b128 v[182:185], v135 offset:6144
	ds_read_b128 v[186:189], v135 offset:7168
	s_add_u32 s6, s18, 0x80f80
	s_addc_u32 s7, s19, 0
	s_mov_b32 m0, s62
	s_nop 0
	global_load_lds_dwordx4 v132, s[6:7]
	s_nop 0
	s_mov_b32 m0, s59
	s_nop 0
	global_load_lds_dwordx4 v131, s[6:7]
	s_barrier
	s_waitcnt lgkmcnt(0)
	s_setprio 1
	v_mfma_f32_16x16x32_bf16 v[126:129], v[138:141], v[154:157], v[126:129]
	v_mfma_f32_16x16x32_bf16 v[126:129], v[142:145], v[158:161], v[126:129]
	v_mfma_f32_16x16x32_bf16 v[122:125], v[150:153], v[158:161], v[122:125]
	v_mfma_f32_16x16x32_bf16 v[122:125], v[146:149], v[154:157], v[122:125]
	v_mfma_f32_16x16x32_bf16 v[114:117], v[146:149], v[162:165], v[114:117]
	v_mfma_f32_16x16x32_bf16 v[114:117], v[150:153], v[170:173], v[114:117]
	v_mfma_f32_16x16x32_bf16 v[118:121], v[142:145], v[170:173], v[118:121]
	v_mfma_f32_16x16x32_bf16 v[118:121], v[138:141], v[162:165], v[118:121]
	v_mfma_f32_16x16x32_bf16 v[110:113], v[138:141], v[174:177], v[110:113]
	v_mfma_f32_16x16x32_bf16 v[110:113], v[142:145], v[178:181], v[110:113]
	v_mfma_f32_16x16x32_bf16 v[106:109], v[150:153], v[178:181], v[106:109]
	v_mfma_f32_16x16x32_bf16 v[106:109], v[146:149], v[174:177], v[106:109]
	v_mfma_f32_16x16x32_bf16 v[98:101], v[146:149], v[182:185], v[98:101]
	v_mfma_f32_16x16x32_bf16 v[98:101], v[150:153], v[186:189], v[98:101]
	v_mfma_f32_16x16x32_bf16 v[102:105], v[142:145], v[186:189], v[102:105]
	v_mfma_f32_16x16x32_bf16 v[102:105], v[138:141], v[182:185], v[102:105]
	s_setprio 0
	s_barrier
	ds_read_b128 v[220:223], v136 offset:16384
	ds_read_b128 v[224:227], v136 offset:17408
	ds_read_b128 v[228:231], v136 offset:18432
	ds_read_b128 v[232:235], v136 offset:19456
	s_barrier
	s_waitcnt lgkmcnt(0)
	s_setprio 1
	v_mfma_f32_16x16x32_bf16 v[94:97], v[220:223], v[154:157], v[94:97]
	v_mfma_f32_16x16x32_bf16 v[94:97], v[224:227], v[158:161], v[94:97]
	v_mfma_f32_16x16x32_bf16 v[90:93], v[232:235], v[158:161], v[90:93]
	v_mfma_f32_16x16x32_bf16 v[90:93], v[228:231], v[154:157], v[90:93]
	v_mfma_f32_16x16x32_bf16 v[82:85], v[228:231], v[162:165], v[82:85]
	v_mfma_f32_16x16x32_bf16 v[82:85], v[232:235], v[170:173], v[82:85]
	v_mfma_f32_16x16x32_bf16 v[86:89], v[224:227], v[170:173], v[86:89]
	v_mfma_f32_16x16x32_bf16 v[86:89], v[220:223], v[162:165], v[86:89]
	v_mfma_f32_16x16x32_bf16 v[78:81], v[220:223], v[174:177], v[78:81]
	v_mfma_f32_16x16x32_bf16 v[78:81], v[224:227], v[178:181], v[78:81]
	v_mfma_f32_16x16x32_bf16 v[74:77], v[232:235], v[178:181], v[74:77]
	v_mfma_f32_16x16x32_bf16 v[74:77], v[228:231], v[174:177], v[74:77]
	v_mfma_f32_16x16x32_bf16 v[66:69], v[228:231], v[182:185], v[66:69]
	v_mfma_f32_16x16x32_bf16 v[66:69], v[232:235], v[186:189], v[66:69]
	v_mfma_f32_16x16x32_bf16 v[70:73], v[224:227], v[186:189], v[70:73]
	v_mfma_f32_16x16x32_bf16 v[70:73], v[220:223], v[182:185], v[70:73]
	s_setprio 0
	s_barrier
; #define WAIT_V(n) asm volatile("s_waitcnt vmcnt(" #n ")" ::: "memory")
; #define WAIT_L(n) asm volatile("s_waitcnt lgkmcnt(" #n ")" ::: "memory")
; #define BAR __builtin_amdgcn_s_barrier()
; #define LDA(dst, b, h)                                                                                   \
;   _Pragma("unroll") for (int m = 0; m < 4; ++m) _Pragma("unroll") for (int k = 0; k < 2; ++k) dst[m][k] = \
;       *reinterpret_cast<const bf16x8*>(aRd + ((b) * 2 + (h)) * 16384 + m * 2048 + k * 1024)
; #define LDB(dst, b, h)                                                                                   \
;   _Pragma("unroll") for (int n = 0; n < 2; ++n) _Pragma("unroll") for (int k = 0; k < 2; ++k) dst[n][k] = \
;       *reinterpret_cast<const bf16x8*>(bRd + ((b) * 2 + (h)) * 16384 + n * 2048 + k * 1024)
; template <int EPI> ...
;     ...
;     LDA(At, 0, 1);
;     WAIT_V(4);
;     BAR;
;     WAIT_L(0);
;     MMA(1, 0, At, B0);
;     MMA(1, 1, At, B1);
;     BAR;
;   }
;   {
;     LDB(B0, 1, 0);
;     LDA(At, 1, 0);
;     WAIT_V(2);
;     BAR;
;     WAIT_L(0);
;     MMA(0, 0, At, B0);
	ds_read_b128 v[154:157], v135 offset:16384
	ds_read_b128 v[158:161], v135 offset:17408
	ds_read_b128 v[162:165], v135 offset:18432
	ds_read_b128 v[170:173], v135 offset:19456
	ds_read_b128 v[174:177], v135 offset:20480
	ds_read_b128 v[178:181], v135 offset:21504
	ds_read_b128 v[182:185], v135 offset:22528
	ds_read_b128 v[186:189], v135 offset:23552
	s_waitcnt vmcnt(4)
	s_barrier
	s_waitcnt lgkmcnt(0)
	s_setprio 1
	v_mfma_f32_16x16x32_bf16 v[62:65], v[138:141], v[154:157], v[62:65]
	v_mfma_f32_16x16x32_bf16 v[62:65], v[142:145], v[158:161], v[62:65]
	v_mfma_f32_16x16x32_bf16 v[58:61], v[150:153], v[158:161], v[58:61]
	v_mfma_f32_16x16x32_bf16 v[58:61], v[146:149], v[154:157], v[58:61]
	v_mfma_f32_16x16x32_bf16 v[50:53], v[146:149], v[162:165], v[50:53]
	v_mfma_f32_16x16x32_bf16 v[50:53], v[150:153], v[170:173], v[50:53]
	v_mfma_f32_16x16x32_bf16 v[54:57], v[142:145], v[170:173], v[54:57]
	v_mfma_f32_16x16x32_bf16 v[54:57], v[138:141], v[162:165], v[54:57]
	v_mfma_f32_16x16x32_bf16 v[46:49], v[138:141], v[174:177], v[46:49]
	v_mfma_f32_16x16x32_bf16 v[46:49], v[142:145], v[178:181], v[46:49]
	v_mfma_f32_16x16x32_bf16 v[42:45], v[150:153], v[178:181], v[42:45]
	v_mfma_f32_16x16x32_bf16 v[42:45], v[146:149], v[174:177], v[42:45]
	v_mfma_f32_16x16x32_bf16 v[34:37], v[146:149], v[182:185], v[34:37]
	v_mfma_f32_16x16x32_bf16 v[34:37], v[150:153], v[186:189], v[34:37]
	v_mfma_f32_16x16x32_bf16 v[38:41], v[142:145], v[186:189], v[38:41]
	v_mfma_f32_16x16x32_bf16 v[38:41], v[138:141], v[182:185], v[38:41]
	s_setprio 0
	s_setprio 1
	v_mfma_f32_16x16x32_bf16 v[30:33], v[220:223], v[154:157], v[30:33]
	v_mfma_f32_16x16x32_bf16 v[30:33], v[224:227], v[158:161], v[30:33]
	v_mfma_f32_16x16x32_bf16 v[26:29], v[232:235], v[158:161], v[26:29]
	v_mfma_f32_16x16x32_bf16 v[26:29], v[228:231], v[154:157], v[26:29]
	v_mfma_f32_16x16x32_bf16 v[18:21], v[228:231], v[162:165], v[18:21]
	v_mfma_f32_16x16x32_bf16 v[18:21], v[232:235], v[170:173], v[18:21]
	v_mfma_f32_16x16x32_bf16 v[22:25], v[224:227], v[170:173], v[22:25]
	v_mfma_f32_16x16x32_bf16 v[22:25], v[220:223], v[162:165], v[22:25]
	v_mfma_f32_16x16x32_bf16 v[14:17], v[220:223], v[174:177], v[14:17]
	v_mfma_f32_16x16x32_bf16 v[14:17], v[224:227], v[178:181], v[14:17]
	v_mfma_f32_16x16x32_bf16 v[10:13], v[232:235], v[178:181], v[10:13]
	v_mfma_f32_16x16x32_bf16 v[10:13], v[228:231], v[174:177], v[10:13]
	v_mfma_f32_16x16x32_bf16 v[2:5], v[228:231], v[182:185], v[2:5]
	v_mfma_f32_16x16x32_bf16 v[2:5], v[232:235], v[186:189], v[2:5]
	v_mfma_f32_16x16x32_bf16 v[6:9], v[224:227], v[186:189], v[6:9]
	v_mfma_f32_16x16x32_bf16 v[6:9], v[220:223], v[182:185], v[6:9]
	s_setprio 0
	s_barrier
	ds_read_b128 v[138:141], v136 offset:32768
	ds_read_b128 v[142:145], v136 offset:33792
	ds_read_b128 v[146:149], v136 offset:34816
	ds_read_b128 v[150:153], v136 offset:35840
	ds_read_b128 v[154:157], v135 offset:32768
	ds_read_b128 v[158:161], v135 offset:33792
	ds_read_b128 v[162:165], v135 offset:34816
	ds_read_b128 v[170:173], v135 offset:35840
	ds_read_b128 v[174:177], v135 offset:36864
	ds_read_b128 v[178:181], v135 offset:37888
	ds_read_b128 v[182:185], v135 offset:38912
	ds_read_b128 v[186:189], v135 offset:39936
	s_waitcnt vmcnt(2)
	s_barrier
	s_waitcnt lgkmcnt(0)
	s_setprio 1
	v_mfma_f32_16x16x32_bf16 v[126:129], v[138:141], v[154:157], v[126:129]
	v_mfma_f32_16x16x32_bf16 v[126:129], v[142:145], v[158:161], v[126:129]
	v_mfma_f32_16x16x32_bf16 v[122:125], v[150:153], v[158:161], v[122:125]
	v_mfma_f32_16x16x32_bf16 v[122:125], v[146:149], v[154:157], v[122:125]
	v_mfma_f32_16x16x32_bf16 v[114:117], v[146:149], v[162:165], v[114:117]
	v_mfma_f32_16x16x32_bf16 v[114:117], v[150:153], v[170:173], v[114:117]
	v_mfma_f32_16x16x32_bf16 v[118:121], v[142:145], v[170:173], v[118:121]
	v_mfma_f32_16x16x32_bf16 v[118:121], v[138:141], v[162:165], v[118:121]
	v_mfma_f32_16x16x32_bf16 v[110:113], v[138:141], v[174:177], v[110:113]
	v_mfma_f32_16x16x32_bf16 v[110:113], v[142:145], v[178:181], v[110:113]
	v_mfma_f32_16x16x32_bf16 v[106:109], v[150:153], v[178:181], v[106:109]
	v_mfma_f32_16x16x32_bf16 v[106:109], v[146:149], v[174:177], v[106:109]
	v_mfma_f32_16x16x32_bf16 v[98:101], v[146:149], v[182:185], v[98:101]
	v_mfma_f32_16x16x32_bf16 v[98:101], v[150:153], v[186:189], v[98:101]
	v_mfma_f32_16x16x32_bf16 v[102:105], v[142:145], v[186:189], v[102:105]
	v_mfma_f32_16x16x32_bf16 v[102:105], v[138:141], v[182:185], v[102:105]
	s_setprio 0
	s_barrier
; #define WAIT_V(n) asm volatile("s_waitcnt vmcnt(" #n ")" ::: "memory")
; #define WAIT_L(n) asm volatile("s_waitcnt lgkmcnt(" #n ")" ::: "memory")
; #define BAR __builtin_amdgcn_s_barrier()
; #define LDA(dst, b, h)                                                                                   \
;   _Pragma("unroll") for (int m = 0; m < 4; ++m) _Pragma("unroll") for (int k = 0; k < 2; ++k) dst[m][k] = \
;       *reinterpret_cast<const bf16x8*>(aRd + ((b) * 2 + (h)) * 16384 + m * 2048 + k * 1024)
; #define LDB(dst, b, h)                                                                                   \
;   _Pragma("unroll") for (int n = 0; n < 2; ++n) _Pragma("unroll") for (int k = 0; k < 2; ++k) dst[n][k] = \
;       *reinterpret_cast<const bf16x8*>(bRd + ((b) * 2 + (h)) * 16384 + n * 2048 + k * 1024)
; template <int EPI> ...
;     ...
;     LDB(B1, 1, 1);
;     WAIT_V(0);
;     BAR;
;     WAIT_L(0);
;     MMA(0, 1, At, B1);
;     BAR;
;     LDA(At, 1, 1);
;     BAR;
;     WAIT_L(0);
;     MMA(1, 0, At, B0);
;     MMA(1, 1, At, B1);
;     BAR;
;   }
;   if (wr == 0) BAR;
	ds_read_b128 v[220:223], v136 offset:49152
	ds_read_b128 v[224:227], v136 offset:50176
	ds_read_b128 v[228:231], v136 offset:51200
	ds_read_b128 v[232:235], v136 offset:52224
	s_waitcnt vmcnt(0)
	s_barrier
	s_waitcnt lgkmcnt(0)
	s_setprio 1
	v_mfma_f32_16x16x32_bf16 v[94:97], v[220:223], v[154:157], v[94:97]
	v_mfma_f32_16x16x32_bf16 v[94:97], v[224:227], v[158:161], v[94:97]
	v_mfma_f32_16x16x32_bf16 v[90:93], v[232:235], v[158:161], v[90:93]
	v_mfma_f32_16x16x32_bf16 v[90:93], v[228:231], v[154:157], v[90:93]
	v_mfma_f32_16x16x32_bf16 v[82:85], v[228:231], v[162:165], v[82:85]
	v_mfma_f32_16x16x32_bf16 v[82:85], v[232:235], v[170:173], v[82:85]
	v_mfma_f32_16x16x32_bf16 v[86:89], v[224:227], v[170:173], v[86:89]
	v_mfma_f32_16x16x32_bf16 v[86:89], v[220:223], v[162:165], v[86:89]
	v_mfma_f32_16x16x32_bf16 v[78:81], v[220:223], v[174:177], v[78:81]
	v_mfma_f32_16x16x32_bf16 v[78:81], v[224:227], v[178:181], v[78:81]
	v_mfma_f32_16x16x32_bf16 v[74:77], v[232:235], v[178:181], v[74:77]
	v_mfma_f32_16x16x32_bf16 v[74:77], v[228:231], v[174:177], v[74:77]
	v_mfma_f32_16x16x32_bf16 v[66:69], v[228:231], v[182:185], v[66:69]
	v_mfma_f32_16x16x32_bf16 v[66:69], v[232:235], v[186:189], v[66:69]
	v_mfma_f32_16x16x32_bf16 v[70:73], v[224:227], v[186:189], v[70:73]
	v_mfma_f32_16x16x32_bf16 v[70:73], v[220:223], v[182:185], v[70:73]
	s_setprio 0
	s_barrier
	ds_read_b128 v[154:157], v135 offset:49152
	ds_read_b128 v[158:161], v135 offset:50176
	ds_read_b128 v[162:165], v135 offset:51200
	ds_read_b128 v[170:173], v135 offset:52224
	ds_read_b128 v[174:177], v135 offset:53248
	ds_read_b128 v[178:181], v135 offset:54272
	ds_read_b128 v[182:185], v135 offset:55296
	ds_read_b128 v[186:189], v135 offset:56320
	s_barrier
	s_waitcnt lgkmcnt(0)
	s_setprio 1
	v_mfma_f32_16x16x32_bf16 v[62:65], v[138:141], v[154:157], v[62:65]
	v_mfma_f32_16x16x32_bf16 v[62:65], v[142:145], v[158:161], v[62:65]
	v_mfma_f32_16x16x32_bf16 v[58:61], v[150:153], v[158:161], v[58:61]
	v_mfma_f32_16x16x32_bf16 v[58:61], v[146:149], v[154:157], v[58:61]
	v_mfma_f32_16x16x32_bf16 v[50:53], v[146:149], v[162:165], v[50:53]
	v_mfma_f32_16x16x32_bf16 v[50:53], v[150:153], v[170:173], v[50:53]
	v_mfma_f32_16x16x32_bf16 v[54:57], v[142:145], v[170:173], v[54:57]
	v_mfma_f32_16x16x32_bf16 v[54:57], v[138:141], v[162:165], v[54:57]
	v_mfma_f32_16x16x32_bf16 v[46:49], v[138:141], v[174:177], v[46:49]
	v_mfma_f32_16x16x32_bf16 v[46:49], v[142:145], v[178:181], v[46:49]
	v_mfma_f32_16x16x32_bf16 v[42:45], v[150:153], v[178:181], v[42:45]
	v_mfma_f32_16x16x32_bf16 v[42:45], v[146:149], v[174:177], v[42:45]
	v_mfma_f32_16x16x32_bf16 v[34:37], v[146:149], v[182:185], v[34:37]
	v_mfma_f32_16x16x32_bf16 v[34:37], v[150:153], v[186:189], v[34:37]
	v_mfma_f32_16x16x32_bf16 v[38:41], v[142:145], v[186:189], v[38:41]
	v_mfma_f32_16x16x32_bf16 v[38:41], v[138:141], v[182:185], v[38:41]
	s_setprio 0
	s_setprio 1
	v_mfma_f32_16x16x32_bf16 v[30:33], v[220:223], v[154:157], v[30:33]
	v_mfma_f32_16x16x32_bf16 v[30:33], v[224:227], v[158:161], v[30:33]
	v_mfma_f32_16x16x32_bf16 v[26:29], v[232:235], v[158:161], v[26:29]
	v_mfma_f32_16x16x32_bf16 v[26:29], v[228:231], v[154:157], v[26:29]
	v_mfma_f32_16x16x32_bf16 v[18:21], v[228:231], v[162:165], v[18:21]
	v_mfma_f32_16x16x32_bf16 v[18:21], v[232:235], v[170:173], v[18:21]
	v_mfma_f32_16x16x32_bf16 v[22:25], v[224:227], v[170:173], v[22:25]
	v_mfma_f32_16x16x32_bf16 v[22:25], v[220:223], v[162:165], v[22:25]
	v_mfma_f32_16x16x32_bf16 v[14:17], v[220:223], v[174:177], v[14:17]
	v_mfma_f32_16x16x32_bf16 v[14:17], v[224:227], v[178:181], v[14:17]
	v_mfma_f32_16x16x32_bf16 v[10:13], v[232:235], v[178:181], v[10:13]
	v_mfma_f32_16x16x32_bf16 v[10:13], v[228:231], v[174:177], v[10:13]
	v_mfma_f32_16x16x32_bf16 v[2:5], v[228:231], v[182:185], v[2:5]
	v_mfma_f32_16x16x32_bf16 v[2:5], v[232:235], v[186:189], v[2:5]
	v_mfma_f32_16x16x32_bf16 v[6:9], v[224:227], v[186:189], v[6:9]
	v_mfma_f32_16x16x32_bf16 v[6:9], v[220:223], v[182:185], v[6:9]
	s_setprio 0
	s_movk_i32 s6, 0x100
	v_cmp_gt_u32_e32 vcc, s6, v133
	s_barrier
	s_and_saveexec_b64 s[12:13], vcc
	s_cbranch_execz .LBB0_418
	s_barrier
